# GEMM k-loop unrolled x2 over the LDS stages (all LDS bases per-tile constants, stage offsets literal: no VALU address math left in the loop); conv epilogue muls packed
# speedup vs baseline: 1.0058x; 1.0005x over previous
.LBB0_637:
	s_and_b64 s[2:3], s[8:9], exec
	v_readlane_b32 s2, v255, 26
	v_readlane_b32 s4, v255, 30
	v_readlane_b32 s3, v255, 27
	v_readlane_b32 s5, v255, 31
	s_cselect_b32 s24, s5, s3
	s_cselect_b32 s28, s4, s2
	v_readlane_b32 s2, v255, 24
	v_readlane_b32 s4, v255, 32
	v_readlane_b32 s3, v255, 25
	v_readlane_b32 s5, v255, 33
	s_cselect_b32 s29, s5, s3
	s_cselect_b32 s34, s4, s2
	v_readlane_b32 s2, v255, 23
	v_readlane_b32 s3, v255, 43
	s_cselect_b32 s14, s3, s2
	v_readlane_b32 s2, v255, 39
	s_cselect_b32 s39, s2, 0
	v_readlane_b32 s2, v255, 18
	v_readlane_b32 s3, v255, 40
	s_cselect_b32 s44, s3, s2
	s_lshl_b32 s45, s15, 8
	s_mul_i32 s2, s15, 0xfe
	s_add_i32 s45, s45, s39
	s_lshl_b32 s6, s47, 8
	s_add_i32 s4, s2, -1
	s_cmp_eq_u32 s44, 7
	s_cselect_b64 vcc, -1, 0
	s_and_b64 s[2:3], vcc, exec
	s_cselect_b32 s2, 0, s45
	s_cselect_b32 s40, s4, 0
	s_ashr_i32 s3, s2, 31
	v_mov_b32_e32 v175, v163
	s_mul_i32 s3, s3, s14
	s_mul_hi_u32 s4, s2, s14
	s_ashr_i32 s7, s6, 31
	s_add_i32 s3, s4, s3
	s_waitcnt vmcnt(1)
	v_ashrrev_i32_e32 v10, 6, v175
	s_waitcnt vmcnt(0)
	v_bfe_u32 v14, v175, 3, 3
	s_mul_i32 s2, s2, s14
	s_mul_i32 s4, s7, s14
	s_mul_hi_u32 s5, s6, s14
	v_lshl_or_b32 v6, v10, 5, v14
	s_add_i32 s5, s5, s4
	v_and_b32_e32 v0, 63, v175
	s_lshl_b64 s[2:3], s[2:3], 1
	s_mul_i32 s4, s6, s14
	s_add_u32 s2, s28, s2
	v_lshlrev_b32_e32 v176, 4, v0
	v_add_u32_e32 v0, s40, v6
	s_addc_u32 s3, s24, s3
	s_lshl_b64 s[4:5], s[4:5], 1
	v_med3_i32 v0, v0, 0, v211
	s_add_u32 s4, s34, s4
	v_cndmask_b32_e32 v0, v6, v0, vcc
	s_addc_u32 s5, s29, s5
	v_bfe_u32 v223, v175, 4, 2
	v_mad_u64_u32 v[166:167], s[28:29], v0, s14, 0
	v_xor_b32_e32 v4, v223, v175
	v_ashrrev_i32_e32 v2, 31, v0
	v_mov_b32_e32 v0, v167
	v_mad_u64_u32 v[2:3], s[28:29], v2, s14, v[0:1]
	v_lshlrev_b32_e32 v0, 3, v4
	v_lshlrev_b32_e32 v15, 2, v10
	v_and_b32_e32 v0, 56, v0
	v_lshlrev_b32_e32 v177, 12, v10
	v_lshlrev_b32_e32 v130, 1, v0
	v_ashrrev_i32_e32 v0, 31, v10
	v_or_b32_e32 v17, v176, v177
	v_or_b32_e32 v18, 1, v15
	v_and_b32_e32 v174, 3, v10
	v_mul_lo_u32 v16, v0, s14
	v_readfirstlane_b32 s15, v17
	v_add_u32_e32 v0, 0x8000, v17
	v_lshl_or_b32 v10, v18, 3, v14
	v_mov_b32_e32 v167, v2
	v_mad_u64_u32 v[168:169], s[28:29], v6, s14, 0
	s_mov_b32 m0, s15
	v_readfirstlane_b32 s15, v0
	v_add_u32_e32 v0, s40, v10
	v_lshl_add_u64 v[2:3], v[166:167], 1, s[2:3]
	v_mov_b32_e32 v131, v1
	v_add_u32_e32 v169, v169, v16
	v_med3_i32 v0, v0, 0, v211
	v_lshl_add_u64 v[4:5], v[2:3], 0, v[130:131]
	v_lshl_add_u64 v[6:7], v[168:169], 1, s[4:5]
	v_cndmask_b32_e32 v0, v10, v0, vcc
	v_lshl_add_u64 v[8:9], v[6:7], 0, v[130:131]
	global_load_lds_dwordx4 v[4:5], off
	s_mov_b32 m0, s15
	v_lshrrev_b32_e32 v4, 1, v10
	v_mad_u64_u32 v[170:171], s[28:29], v0, s14, 0
	global_load_lds_dwordx4 v[8:9], off
	v_xor_b32_e32 v8, v4, v175
	v_ashrrev_i32_e32 v4, 31, v0
	v_mov_b32_e32 v0, v171
	v_mad_u64_u32 v[4:5], s[28:29], v4, s14, v[0:1]
	v_lshlrev_b32_e32 v0, 3, v8
	v_lshlrev_b32_e32 v178, 10, v18
	v_mov_b32_e32 v171, v4
	v_and_b32_e32 v0, 56, v0
	v_mad_u64_u32 v[172:173], s[28:29], v10, s14, 0
	v_or_b32_e32 v18, v176, v178
	v_lshl_add_u64 v[4:5], v[170:171], 1, s[2:3]
	v_lshlrev_b32_e32 v132, 1, v0
	v_mov_b32_e32 v133, v1
	v_add_u32_e32 v173, v173, v16
	v_readfirstlane_b32 s15, v18
	v_add_u32_e32 v0, 0x8000, v18
	v_lshl_add_u64 v[8:9], v[4:5], 0, v[132:133]
	v_lshl_add_u64 v[10:11], v[172:173], 1, s[4:5]
	s_mov_b32 m0, s15
	v_readfirstlane_b32 s15, v0
	s_waitcnt lgkmcnt(0)
	v_lshl_add_u64 v[12:13], v[10:11], 0, v[132:133]
	global_load_lds_dwordx4 v[8:9], off
	s_mov_b32 m0, s15
	v_or_b32_e32 v19, 2, v15
	global_load_lds_dwordx4 v[12:13], off
	v_lshl_or_b32 v12, v19, 3, v14
	v_add_u32_e32 v0, s40, v12
	v_med3_i32 v0, v0, 0, v211
	v_cndmask_b32_e32 v0, v12, v0, vcc
	v_lshrrev_b32_e32 v8, 1, v12
	v_mad_u64_u32 v[154:155], s[28:29], v0, s14, 0
	v_xor_b32_e32 v13, v8, v175
	v_ashrrev_i32_e32 v8, 31, v0
	v_mov_b32_e32 v0, v155
	v_mad_u64_u32 v[8:9], s[28:29], v8, s14, v[0:1]
	v_lshlrev_b32_e32 v0, 3, v13
	v_lshlrev_b32_e32 v179, 10, v19
	v_mov_b32_e32 v155, v8
	v_and_b32_e32 v0, 56, v0
	v_or_b32_e32 v19, v176, v179
	v_lshl_add_u64 v[8:9], v[154:155], 1, s[2:3]
	v_lshlrev_b32_e32 v0, 1, v0
	v_readfirstlane_b32 s15, v19
	v_lshl_add_u64 v[8:9], v[8:9], 0, v[0:1]
	v_mad_u64_u32 v[156:157], s[28:29], v12, s14, 0
	s_mov_b32 m0, s15
	v_add_u32_e32 v157, v157, v16
	global_load_lds_dwordx4 v[8:9], off
	v_add_u32_e32 v8, 0x8000, v19
	v_lshl_add_u64 v[12:13], v[156:157], 1, s[4:5]
	v_readfirstlane_b32 s15, v8
	v_lshl_add_u64 v[12:13], v[12:13], 0, v[0:1]
	s_mov_b32 m0, s15
	v_or_b32_e32 v15, 3, v15
	global_load_lds_dwordx4 v[12:13], off
	v_lshl_or_b32 v12, v15, 3, v14
	v_add_u32_e32 v8, s40, v12
	v_med3_i32 v8, v8, 0, v211
	v_cndmask_b32_e32 v8, v12, v8, vcc
	v_lshrrev_b32_e32 v9, 1, v12
	v_mad_u64_u32 v[158:159], s[28:29], v8, s14, 0
	v_xor_b32_e32 v13, v9, v175
	v_ashrrev_i32_e32 v9, 31, v8
	v_mov_b32_e32 v8, v159
	v_mad_u64_u32 v[8:9], s[28:29], v9, s14, v[8:9]
	v_lshlrev_b32_e32 v13, 3, v13
	v_lshlrev_b32_e32 v180, 10, v15
	v_mov_b32_e32 v159, v8
	v_and_b32_e32 v13, 56, v13
	v_or_b32_e32 v14, v176, v180
	v_lshl_add_u64 v[8:9], v[158:159], 1, s[2:3]
	v_lshlrev_b32_e32 v160, 1, v13
	v_mov_b32_e32 v161, v1
	v_readfirstlane_b32 s15, v14
	v_lshl_add_u64 v[8:9], v[8:9], 0, v[160:161]
	v_mad_u64_u32 v[164:165], s[28:29], v12, s14, 0
	s_mov_b32 m0, s15
	v_add_u32_e32 v165, v165, v16
	global_load_lds_dwordx4 v[8:9], off
	v_add_u32_e32 v8, 0x8000, v14
	s_cmpk_gt_u32 s14, 0x7f
	v_lshl_add_u64 v[12:13], v[164:165], 1, s[4:5]
	v_readfirstlane_b32 s15, v8
	s_cselect_b32 s34, 0x80, 0
	v_add_u32_e32 v8, 0x10000, v17
	v_lshl_add_u64 v[12:13], v[12:13], 0, v[160:161]
	s_mov_b32 m0, s15
	v_lshl_add_u64 v[2:3], v[2:3], 0, s[34:35]
	v_readfirstlane_b32 s15, v8
	global_load_lds_dwordx4 v[12:13], off
	v_lshl_add_u64 v[2:3], v[2:3], 0, v[130:131]
	s_mov_b32 m0, s15
	v_mov_b32_e32 v127, 0
	v_mov_b32_e32 v128, 0
	v_mov_b32_e32 v129, 0
	v_mov_b32_e32 v122, 0
	v_mov_b32_e32 v123, 0
	v_mov_b32_e32 v124, 0
	v_mov_b32_e32 v125, 0
	v_mov_b32_e32 v118, 0
	v_mov_b32_e32 v119, 0
	v_mov_b32_e32 v120, 0
	v_mov_b32_e32 v121, 0
	v_mov_b32_e32 v114, 0
	v_mov_b32_e32 v115, 0
	v_mov_b32_e32 v116, 0
	v_mov_b32_e32 v117, 0
	v_mov_b32_e32 v110, 0
	v_mov_b32_e32 v111, 0
	v_mov_b32_e32 v112, 0
	v_mov_b32_e32 v113, 0
	v_mov_b32_e32 v106, 0
	v_mov_b32_e32 v107, 0
	v_mov_b32_e32 v108, 0
	v_mov_b32_e32 v109, 0
	v_mov_b32_e32 v102, 0
	v_mov_b32_e32 v103, 0
	v_mov_b32_e32 v104, 0
	v_mov_b32_e32 v105, 0
	v_mov_b32_e32 v98, 0
	v_mov_b32_e32 v99, 0
	v_mov_b32_e32 v100, 0
	v_mov_b32_e32 v101, 0
	v_mov_b32_e32 v94, 0
	v_mov_b32_e32 v95, 0
	v_mov_b32_e32 v96, 0
	v_mov_b32_e32 v97, 0
	v_mov_b32_e32 v90, 0
	v_mov_b32_e32 v91, 0
	v_mov_b32_e32 v92, 0
	v_mov_b32_e32 v93, 0
	v_mov_b32_e32 v86, 0
	v_mov_b32_e32 v87, 0
	v_mov_b32_e32 v88, 0
	v_mov_b32_e32 v89, 0
	v_mov_b32_e32 v82, 0
	v_mov_b32_e32 v83, 0
	v_mov_b32_e32 v84, 0
	v_mov_b32_e32 v85, 0
	v_mov_b32_e32 v78, 0
	v_mov_b32_e32 v79, 0
	v_mov_b32_e32 v80, 0
	v_mov_b32_e32 v81, 0
	v_mov_b32_e32 v74, 0
	v_mov_b32_e32 v75, 0
	v_mov_b32_e32 v76, 0
	v_mov_b32_e32 v77, 0
	v_mov_b32_e32 v70, 0
	v_mov_b32_e32 v71, 0
	v_mov_b32_e32 v72, 0
	v_mov_b32_e32 v73, 0
	v_mov_b32_e32 v66, 0
	v_mov_b32_e32 v67, 0
	v_mov_b32_e32 v68, 0
	v_mov_b32_e32 v69, 0
	v_mov_b32_e32 v62, 0
	v_mov_b32_e32 v63, 0
	v_mov_b32_e32 v64, 0
	v_mov_b32_e32 v65, 0
	v_mov_b32_e32 v58, 0
	v_mov_b32_e32 v59, 0
	v_mov_b32_e32 v60, 0
	v_mov_b32_e32 v61, 0
	v_mov_b32_e32 v54, 0
	v_mov_b32_e32 v55, 0
	v_mov_b32_e32 v56, 0
	v_mov_b32_e32 v57, 0
	v_mov_b32_e32 v50, 0
	v_mov_b32_e32 v51, 0
	v_mov_b32_e32 v52, 0
	v_mov_b32_e32 v53, 0
	v_mov_b32_e32 v46, 0
	v_mov_b32_e32 v47, 0
	v_mov_b32_e32 v48, 0
	v_mov_b32_e32 v49, 0
	v_mov_b32_e32 v42, 0
	v_mov_b32_e32 v43, 0
	v_mov_b32_e32 v44, 0
	v_mov_b32_e32 v45, 0
	v_mov_b32_e32 v34, 0
	v_mov_b32_e32 v35, 0
	v_mov_b32_e32 v36, 0
	v_mov_b32_e32 v37, 0
	v_mov_b32_e32 v30, 0
	v_mov_b32_e32 v31, 0
	v_mov_b32_e32 v32, 0
	v_mov_b32_e32 v33, 0
	v_mov_b32_e32 v38, 0
	v_mov_b32_e32 v39, 0
	v_mov_b32_e32 v40, 0
	v_mov_b32_e32 v41, 0
	v_mov_b32_e32 v26, 0
	v_mov_b32_e32 v27, 0
	v_mov_b32_e32 v28, 0
	v_mov_b32_e32 v29, 0
	v_mov_b32_e32 v22, 0
	v_mov_b32_e32 v23, 0
	v_mov_b32_e32 v24, 0
	v_mov_b32_e32 v25, 0
	v_mov_b32_e32 v19, 0
	v_mov_b32_e32 v20, 0
	v_mov_b32_e32 v21, 0
	v_mov_b32_e32 v14, 0
	v_mov_b32_e32 v15, 0
	v_mov_b32_e32 v16, 0
	v_mov_b32_e32 v12, 0
	v_mov_b32_e32 v13, 0
	s_waitcnt vmcnt(0)
	s_waitcnt vmcnt(0) lgkmcnt(0)
	s_barrier
	global_load_lds_dwordx4 v[2:3], off
	v_add_u32_e32 v2, 0x18000, v17
	v_lshl_add_u64 v[6:7], v[6:7], 0, s[34:35]
	v_readfirstlane_b32 s15, v2
	v_lshl_add_u64 v[6:7], v[6:7], 0, v[130:131]
	s_mov_b32 m0, s15
	v_lshl_add_u64 v[2:3], v[4:5], 0, s[34:35]
	global_load_lds_dwordx4 v[6:7], off
	v_add_u32_e32 v6, 0x10000, v18
	v_lshl_add_u64 v[2:3], v[2:3], 0, v[132:133]
	v_readfirstlane_b32 s15, v6
	s_mov_b32 m0, s15
	v_lshl_add_u64 v[4:5], v[10:11], 0, s[34:35]
	global_load_lds_dwordx4 v[2:3], off
	v_add_u32_e32 v2, 0x18000, v18
	v_lshl_add_u64 v[4:5], v[4:5], 0, v[132:133]
	v_readfirstlane_b32 s15, v2
	s_mov_b32 m0, s15
	v_and_b32_e32 v134, 15, v175
	global_load_lds_dwordx4 v[4:5], off
	v_ashrrev_i32_e32 v2, 1, v175
	s_movk_i32 s15, 0xff80
	v_mov_b32_e32 v5, 0
	v_and_or_b32 v225, v2, s15, v134
	v_lshlrev_b32_e32 v224, 6, v174
	s_cmp_lt_u32 s14, 64
	v_readlane_b32 s51, v255, 37
	v_readlane_b32 s52, v255, 38
	s_cbranch_scc1 .Lgemm_skip_zero_a
	v_lshrrev_b32_e32 v10, 1, v134
	v_or_b32_e32 v2, v224, v134
	v_lshlrev_b32_e32 v182, 7, v2
	v_xor_b32_e32 v2, v223, v10
	v_lshlrev_b32_e32 v181, 7, v225
	v_lshlrev_b32_e32 v183, 4, v2
	v_or_b32_e32 v11, v181, v183
	v_or_b32_e32 v244, v182, v183
	v_lshl_add_u32 v240, v166, 1, v130
	v_lshl_add_u32 v241, v168, 1, v130
	v_lshl_add_u32 v242, v170, 1, v132
	v_lshl_add_u32 v243, v172, 1, v132
	ds_read_b128 v[150:153], v11
	ds_read_b128 v[146:149], v11 offset:2048
	ds_read_b128 v[142:145], v244 offset:32768
	ds_read_b128 v[138:141], v244 offset:34816
	ds_read_b128 v[134:137], v244 offset:36864
	ds_read_b128 v[200:203], v11 offset:4096
	ds_read_b128 v[130:133], v244 offset:38912
	ds_read_b128 v[236:239], v11 offset:6144
	s_lshr_b32 s14, s14, 6
	v_bitop3_b32 v10, v223, v10, 4 bitop3:0x36
	v_mov_b32_e32 v126, 0
	s_add_i32 s15, s14, -1
	v_lshlrev_b32_e32 v184, 4, v10
	v_add_u32_e32 v227, v181, v183
	v_add_u32_e32 v229, v181, v184
	v_add_u32_e32 v228, v182, v184
	v_add_u32_e32 v226, v182, v183
	v_add_u32_e32 v234, 0x10000, v227
	v_add_u32_e32 v186, 0x10000, v229
	v_add_u32_e32 v187, 0x10000, v228
	v_add_u32_e32 v233, 0x10000, v226
	s_mov_b32 s24, 0
	s_mov_b32 s28, 0
	v_mov_b32_e32 v161, v1
	v_lshl_add_u64 v[154:155], v[154:155], 1, v[0:1]
	v_lshl_add_u64 v[156:157], v[156:157], 1, v[0:1]
	v_lshl_add_u64 v[158:159], v[158:159], 1, v[160:161]
	v_lshl_add_u64 v[164:165], v[164:165], 1, v[160:161]
	v_readfirstlane_b32 s100, v179
	v_readfirstlane_b32 s101, v180
	v_readfirstlane_b32 s32, v178
	v_readfirstlane_b32 s41, v177
	s_lshl_b32 s32, s32, 16
	s_or_b32 s32, s32, s41
	v_mov_b32_e32 v18, v126
	v_mov_b32_e32 v17, v126
	v_mov_b32_e32 v10, v126
	v_mov_b32_e32 v11, v126
	v_mov_b32_e32 v6, v126
	v_mov_b32_e32 v7, v126
	v_mov_b32_e32 v8, v126
	v_mov_b32_e32 v9, v126
	v_mov_b32_e32 v2, v126
	v_mov_b32_e32 v3, v126
	v_mov_b32_e32 v4, v126
	v_mov_b32_e32 v5, v126
.LBB0_639:
	s_add_i32 s41, s28, 1
	s_cmp_lt_u32 s41, s14
	s_cselect_b32 s29, s41, s28
	s_lshl_b32 s34, s29, 6
	s_lshl_b64 s[42:43], s[34:35], 1
	s_add_u32 s48, s2, s42
	s_addc_u32 s49, s3, s43
	s_add_u32 s42, s4, s42
	s_waitcnt lgkmcnt(5)
	v_mfma_f32_16x16x32_bf16 v[126:129], v[142:145], v[150:153], v[126:129]
	s_addc_u32 s43, s5, s43
	v_mfma_f32_16x16x32_bf16 v[110:113], v[142:145], v[146:149], v[110:113]
	s_add_i32 m0, s100, 0x10000
	s_waitcnt lgkmcnt(4)
	v_mfma_f32_16x16x32_bf16 v[122:125], v[138:141], v[150:153], v[122:125]
	s_add_i32 s28, s28, 2
	s_min_i32 s28, s28, s15
	s_lshl_b32 s28, s28, 6
	v_mfma_f32_16x16x32_bf16 v[106:109], v[138:141], v[146:149], v[106:109]
	global_load_lds_dwordx4 v154, s[48:49]
	s_add_i32 m0, m0, 0x8000
	s_waitcnt lgkmcnt(3)
	v_mfma_f32_16x16x32_bf16 v[118:121], v[134:137], v[150:153], v[118:121]
	v_mfma_f32_16x16x32_bf16 v[102:105], v[134:137], v[146:149], v[102:105]
	global_load_lds_dwordx4 v156, s[42:43]
	s_add_i32 m0, s101, 0x10000
	s_waitcnt lgkmcnt(1)
	v_mfma_f32_16x16x32_bf16 v[114:117], v[130:133], v[150:153], v[114:117]
	ds_read_b128 v[150:153], v227 offset:8192
	v_mfma_f32_16x16x32_bf16 v[98:101], v[130:133], v[146:149], v[98:101]
	ds_read_b128 v[146:149], v227 offset:10240
	v_mfma_f32_16x16x32_bf16 v[94:97], v[142:145], v[200:203], v[94:97]
	v_mfma_f32_16x16x32_bf16 v[90:93], v[138:141], v[200:203], v[90:93]
	global_load_lds_dwordx4 v158, s[48:49]
	s_add_i32 m0, m0, 0x8000
	v_mfma_f32_16x16x32_bf16 v[86:89], v[134:137], v[200:203], v[86:89]
	v_mfma_f32_16x16x32_bf16 v[82:85], v[130:133], v[200:203], v[82:85]
	ds_read_b128 v[200:203], v227 offset:12288
	s_waitcnt lgkmcnt(3)
	v_mfma_f32_16x16x32_bf16 v[78:81], v[142:145], v[236:239], v[78:81]
	global_load_lds_dwordx4 v164, s[42:43]
	v_mfma_f32_16x16x32_bf16 v[74:77], v[138:141], v[236:239], v[74:77]
	v_mfma_f32_16x16x32_bf16 v[70:73], v[134:137], v[236:239], v[70:73]
	s_ashr_i32 s29, s28, 31
	v_mfma_f32_16x16x32_bf16 v[66:69], v[130:133], v[236:239], v[66:69]
	ds_read_b128 v[236:239], v227 offset:14336
	s_waitcnt lgkmcnt(3)
	v_mfma_f32_16x16x32_bf16 v[62:65], v[142:145], v[150:153], v[62:65]
	v_mfma_f32_16x16x32_bf16 v[58:61], v[138:141], v[150:153], v[58:61]
	v_mfma_f32_16x16x32_bf16 v[54:57], v[134:137], v[150:153], v[54:57]
	v_mfma_f32_16x16x32_bf16 v[50:53], v[130:133], v[150:153], v[50:53]
	ds_read_b128 v[150:153], v229
	s_waitcnt lgkmcnt(3)
	v_mfma_f32_16x16x32_bf16 v[46:49], v[142:145], v[146:149], v[46:49]
	v_mfma_f32_16x16x32_bf16 v[42:45], v[138:141], v[146:149], v[42:45]
	v_mfma_f32_16x16x32_bf16 v[34:37], v[134:137], v[146:149], v[34:37]
	v_mfma_f32_16x16x32_bf16 v[30:33], v[130:133], v[146:149], v[30:33]
	ds_read_b128 v[146:149], v229 offset:2048
	s_waitcnt lgkmcnt(3)
	v_mfma_f32_16x16x32_bf16 v[38:41], v[142:145], v[200:203], v[38:41]
	s_waitcnt lgkmcnt(2)
	v_mfma_f32_16x16x32_bf16 v[14:17], v[142:145], v[236:239], v[14:17]
	ds_read_b128 v[142:145], v228 offset:32768
	v_mfma_f32_16x16x32_bf16 v[26:29], v[138:141], v[200:203], v[26:29]
	v_mfma_f32_16x16x32_bf16 v[10:13], v[138:141], v[236:239], v[10:13]
	ds_read_b128 v[138:141], v228 offset:34816
	v_mfma_f32_16x16x32_bf16 v[22:25], v[134:137], v[200:203], v[22:25]
	v_mfma_f32_16x16x32_bf16 v[6:9], v[134:137], v[236:239], v[6:9]
	ds_read_b128 v[134:137], v228 offset:36864
	v_mfma_f32_16x16x32_bf16 v[18:21], v[130:133], v[200:203], v[18:21]
	ds_read_b128 v[200:203], v229 offset:4096
	v_mfma_f32_16x16x32_bf16 v[2:5], v[130:133], v[236:239], v[2:5]
	ds_read_b128 v[130:133], v228 offset:38912
	ds_read_b128 v[236:239], v229 offset:6144
	s_waitcnt lgkmcnt(5)
	v_mfma_f32_16x16x32_bf16 v[126:129], v[142:145], v[150:153], v[126:129]
	v_mfma_f32_16x16x32_bf16 v[110:113], v[142:145], v[146:149], v[110:113]
	s_waitcnt lgkmcnt(4)
	v_mfma_f32_16x16x32_bf16 v[122:125], v[138:141], v[150:153], v[122:125]
	v_mfma_f32_16x16x32_bf16 v[106:109], v[138:141], v[146:149], v[106:109]
	s_waitcnt lgkmcnt(3)
	v_mfma_f32_16x16x32_bf16 v[118:121], v[134:137], v[150:153], v[118:121]
	v_mfma_f32_16x16x32_bf16 v[102:105], v[134:137], v[146:149], v[102:105]
	s_waitcnt lgkmcnt(1)
	v_mfma_f32_16x16x32_bf16 v[114:117], v[130:133], v[150:153], v[114:117]
	ds_read_b128 v[150:153], v229 offset:8192
	v_mfma_f32_16x16x32_bf16 v[98:101], v[130:133], v[146:149], v[98:101]
	ds_read_b128 v[146:149], v229 offset:10240
	v_mfma_f32_16x16x32_bf16 v[94:97], v[142:145], v[200:203], v[94:97]
	v_mfma_f32_16x16x32_bf16 v[90:93], v[138:141], v[200:203], v[90:93]
	v_mfma_f32_16x16x32_bf16 v[86:89], v[134:137], v[200:203], v[86:89]
	v_mfma_f32_16x16x32_bf16 v[82:85], v[130:133], v[200:203], v[82:85]
	ds_read_b128 v[200:203], v229 offset:12288
	s_waitcnt lgkmcnt(3)
	v_mfma_f32_16x16x32_bf16 v[78:81], v[142:145], v[236:239], v[78:81]
	v_mfma_f32_16x16x32_bf16 v[74:77], v[138:141], v[236:239], v[74:77]
	v_mfma_f32_16x16x32_bf16 v[70:73], v[134:137], v[236:239], v[70:73]
	s_lshl_b64 s[28:29], s[28:29], 1
	s_add_u32 s48, s2, s28
	s_addc_u32 s49, s3, s29
	s_add_u32 s42, s4, s28
	s_addc_u32 s43, s5, s29
	s_and_b32 m0, s32, 0xffff
	v_mfma_f32_16x16x32_bf16 v[66:69], v[130:133], v[236:239], v[66:69]
	ds_read_b128 v[236:239], v229 offset:14336
	s_waitcnt lgkmcnt(3)
	v_mfma_f32_16x16x32_bf16 v[62:65], v[142:145], v[150:153], v[62:65]
	v_mfma_f32_16x16x32_bf16 v[58:61], v[138:141], v[150:153], v[58:61]
	v_mfma_f32_16x16x32_bf16 v[54:57], v[134:137], v[150:153], v[54:57]
	v_mfma_f32_16x16x32_bf16 v[50:53], v[130:133], v[150:153], v[50:53]
	s_waitcnt vmcnt(0) lgkmcnt(0)
	s_barrier
	ds_read_b128 v[150:153], v234
	v_mfma_f32_16x16x32_bf16 v[46:49], v[142:145], v[146:149], v[46:49]
	global_load_lds_dwordx4 v240, s[48:49]
	s_add_i32 m0, m0, 0x8000
	v_mfma_f32_16x16x32_bf16 v[42:45], v[138:141], v[146:149], v[42:45]
	v_mfma_f32_16x16x32_bf16 v[34:37], v[134:137], v[146:149], v[34:37]
	global_load_lds_dwordx4 v241, s[42:43]
	s_lshr_b32 m0, s32, 16
	v_mfma_f32_16x16x32_bf16 v[30:33], v[130:133], v[146:149], v[30:33]
	ds_read_b128 v[146:149], v234 offset:2048
	v_mfma_f32_16x16x32_bf16 v[38:41], v[142:145], v[200:203], v[38:41]
	v_mfma_f32_16x16x32_bf16 v[14:17], v[142:145], v[236:239], v[14:17]
	ds_read_b128 v[142:145], v233 offset:32768
	global_load_lds_dwordx4 v242, s[48:49]
	s_add_i32 m0, m0, 0x8000
	v_mfma_f32_16x16x32_bf16 v[26:29], v[138:141], v[200:203], v[26:29]
	v_mfma_f32_16x16x32_bf16 v[10:13], v[138:141], v[236:239], v[10:13]
	ds_read_b128 v[138:141], v233 offset:34816
	global_load_lds_dwordx4 v243, s[42:43]
	v_mfma_f32_16x16x32_bf16 v[22:25], v[134:137], v[200:203], v[22:25]
	v_mfma_f32_16x16x32_bf16 v[6:9], v[134:137], v[236:239], v[6:9]
	ds_read_b128 v[134:137], v233 offset:36864
	v_mfma_f32_16x16x32_bf16 v[18:21], v[130:133], v[200:203], v[18:21]
	ds_read_b128 v[200:203], v234 offset:4096
	v_mfma_f32_16x16x32_bf16 v[2:5], v[130:133], v[236:239], v[2:5]
	ds_read_b128 v[130:133], v233 offset:38912
	ds_read_b128 v[236:239], v234 offset:6144
	s_cmp_eq_u32 s14, s41
	s_mov_b32 s28, s41
	s_cbranch_scc1 .LBB0_640
	s_add_i32 s41, s28, 1
	s_cmp_lt_u32 s41, s14
	s_cselect_b32 s29, s41, s28
	s_lshl_b32 s34, s29, 6
	s_lshl_b64 s[42:43], s[34:35], 1
	s_add_u32 s48, s2, s42
	s_addc_u32 s49, s3, s43
	s_add_u32 s42, s4, s42
	s_waitcnt lgkmcnt(5)
	v_mfma_f32_16x16x32_bf16 v[126:129], v[142:145], v[150:153], v[126:129]
	s_addc_u32 s43, s5, s43
	v_mfma_f32_16x16x32_bf16 v[110:113], v[142:145], v[146:149], v[110:113]
	s_mov_b32 m0, s100
	s_waitcnt lgkmcnt(4)
	v_mfma_f32_16x16x32_bf16 v[122:125], v[138:141], v[150:153], v[122:125]
	s_add_i32 s28, s28, 2
	s_min_i32 s28, s28, s15
	s_lshl_b32 s28, s28, 6
	v_mfma_f32_16x16x32_bf16 v[106:109], v[138:141], v[146:149], v[106:109]
	global_load_lds_dwordx4 v154, s[48:49]
	s_add_i32 m0, m0, 0x8000
	s_waitcnt lgkmcnt(3)
	v_mfma_f32_16x16x32_bf16 v[118:121], v[134:137], v[150:153], v[118:121]
	v_mfma_f32_16x16x32_bf16 v[102:105], v[134:137], v[146:149], v[102:105]
	global_load_lds_dwordx4 v156, s[42:43]
	s_mov_b32 m0, s101
	s_waitcnt lgkmcnt(1)
	v_mfma_f32_16x16x32_bf16 v[114:117], v[130:133], v[150:153], v[114:117]
	ds_read_b128 v[150:153], v234 offset:8192
	v_mfma_f32_16x16x32_bf16 v[98:101], v[130:133], v[146:149], v[98:101]
	ds_read_b128 v[146:149], v234 offset:10240
	v_mfma_f32_16x16x32_bf16 v[94:97], v[142:145], v[200:203], v[94:97]
	v_mfma_f32_16x16x32_bf16 v[90:93], v[138:141], v[200:203], v[90:93]
	global_load_lds_dwordx4 v158, s[48:49]
	s_add_i32 m0, m0, 0x8000
	v_mfma_f32_16x16x32_bf16 v[86:89], v[134:137], v[200:203], v[86:89]
	v_mfma_f32_16x16x32_bf16 v[82:85], v[130:133], v[200:203], v[82:85]
	ds_read_b128 v[200:203], v234 offset:12288
	s_waitcnt lgkmcnt(3)
	v_mfma_f32_16x16x32_bf16 v[78:81], v[142:145], v[236:239], v[78:81]
	global_load_lds_dwordx4 v164, s[42:43]
	v_mfma_f32_16x16x32_bf16 v[74:77], v[138:141], v[236:239], v[74:77]
	v_mfma_f32_16x16x32_bf16 v[70:73], v[134:137], v[236:239], v[70:73]
	s_ashr_i32 s29, s28, 31
	v_mfma_f32_16x16x32_bf16 v[66:69], v[130:133], v[236:239], v[66:69]
	ds_read_b128 v[236:239], v234 offset:14336
	s_waitcnt lgkmcnt(3)
	v_mfma_f32_16x16x32_bf16 v[62:65], v[142:145], v[150:153], v[62:65]
	v_mfma_f32_16x16x32_bf16 v[58:61], v[138:141], v[150:153], v[58:61]
	v_mfma_f32_16x16x32_bf16 v[54:57], v[134:137], v[150:153], v[54:57]
	v_mfma_f32_16x16x32_bf16 v[50:53], v[130:133], v[150:153], v[50:53]
	ds_read_b128 v[150:153], v186
	s_waitcnt lgkmcnt(3)
	v_mfma_f32_16x16x32_bf16 v[46:49], v[142:145], v[146:149], v[46:49]
	v_mfma_f32_16x16x32_bf16 v[42:45], v[138:141], v[146:149], v[42:45]
	v_mfma_f32_16x16x32_bf16 v[34:37], v[134:137], v[146:149], v[34:37]
	v_mfma_f32_16x16x32_bf16 v[30:33], v[130:133], v[146:149], v[30:33]
	ds_read_b128 v[146:149], v186 offset:2048
	s_waitcnt lgkmcnt(3)
	v_mfma_f32_16x16x32_bf16 v[38:41], v[142:145], v[200:203], v[38:41]
	s_waitcnt lgkmcnt(2)
	v_mfma_f32_16x16x32_bf16 v[14:17], v[142:145], v[236:239], v[14:17]
	ds_read_b128 v[142:145], v187 offset:32768
	v_mfma_f32_16x16x32_bf16 v[26:29], v[138:141], v[200:203], v[26:29]
	v_mfma_f32_16x16x32_bf16 v[10:13], v[138:141], v[236:239], v[10:13]
	ds_read_b128 v[138:141], v187 offset:34816
	v_mfma_f32_16x16x32_bf16 v[22:25], v[134:137], v[200:203], v[22:25]
	v_mfma_f32_16x16x32_bf16 v[6:9], v[134:137], v[236:239], v[6:9]
	ds_read_b128 v[134:137], v187 offset:36864
	v_mfma_f32_16x16x32_bf16 v[18:21], v[130:133], v[200:203], v[18:21]
	ds_read_b128 v[200:203], v186 offset:4096
	v_mfma_f32_16x16x32_bf16 v[2:5], v[130:133], v[236:239], v[2:5]
	ds_read_b128 v[130:133], v187 offset:38912
	ds_read_b128 v[236:239], v186 offset:6144
	s_waitcnt lgkmcnt(5)
	v_mfma_f32_16x16x32_bf16 v[126:129], v[142:145], v[150:153], v[126:129]
	v_mfma_f32_16x16x32_bf16 v[110:113], v[142:145], v[146:149], v[110:113]
	s_waitcnt lgkmcnt(4)
	v_mfma_f32_16x16x32_bf16 v[122:125], v[138:141], v[150:153], v[122:125]
	v_mfma_f32_16x16x32_bf16 v[106:109], v[138:141], v[146:149], v[106:109]
	s_waitcnt lgkmcnt(3)
	v_mfma_f32_16x16x32_bf16 v[118:121], v[134:137], v[150:153], v[118:121]
	v_mfma_f32_16x16x32_bf16 v[102:105], v[134:137], v[146:149], v[102:105]
	s_waitcnt lgkmcnt(1)
	v_mfma_f32_16x16x32_bf16 v[114:117], v[130:133], v[150:153], v[114:117]
	ds_read_b128 v[150:153], v186 offset:8192
	v_mfma_f32_16x16x32_bf16 v[98:101], v[130:133], v[146:149], v[98:101]
	ds_read_b128 v[146:149], v186 offset:10240
	v_mfma_f32_16x16x32_bf16 v[94:97], v[142:145], v[200:203], v[94:97]
	v_mfma_f32_16x16x32_bf16 v[90:93], v[138:141], v[200:203], v[90:93]
	v_mfma_f32_16x16x32_bf16 v[86:89], v[134:137], v[200:203], v[86:89]
	v_mfma_f32_16x16x32_bf16 v[82:85], v[130:133], v[200:203], v[82:85]
	ds_read_b128 v[200:203], v186 offset:12288
	s_waitcnt lgkmcnt(3)
	v_mfma_f32_16x16x32_bf16 v[78:81], v[142:145], v[236:239], v[78:81]
	v_mfma_f32_16x16x32_bf16 v[74:77], v[138:141], v[236:239], v[74:77]
	v_mfma_f32_16x16x32_bf16 v[70:73], v[134:137], v[236:239], v[70:73]
	s_lshl_b64 s[28:29], s[28:29], 1
	s_add_u32 s48, s2, s28
	s_addc_u32 s49, s3, s29
	s_add_u32 s42, s4, s28
	s_addc_u32 s43, s5, s29
	s_and_b32 m0, s32, 0xffff
	s_add_i32 m0, m0, 0x10000
	v_mfma_f32_16x16x32_bf16 v[66:69], v[130:133], v[236:239], v[66:69]
	ds_read_b128 v[236:239], v186 offset:14336
	s_waitcnt lgkmcnt(3)
	v_mfma_f32_16x16x32_bf16 v[62:65], v[142:145], v[150:153], v[62:65]
	v_mfma_f32_16x16x32_bf16 v[58:61], v[138:141], v[150:153], v[58:61]
	v_mfma_f32_16x16x32_bf16 v[54:57], v[134:137], v[150:153], v[54:57]
	v_mfma_f32_16x16x32_bf16 v[50:53], v[130:133], v[150:153], v[50:53]
	s_waitcnt vmcnt(0) lgkmcnt(0)
	s_barrier
	ds_read_b128 v[150:153], v227
	v_mfma_f32_16x16x32_bf16 v[46:49], v[142:145], v[146:149], v[46:49]
	global_load_lds_dwordx4 v240, s[48:49]
	s_add_i32 m0, m0, 0x8000
	v_mfma_f32_16x16x32_bf16 v[42:45], v[138:141], v[146:149], v[42:45]
	v_mfma_f32_16x16x32_bf16 v[34:37], v[134:137], v[146:149], v[34:37]
	global_load_lds_dwordx4 v241, s[42:43]
	s_lshr_b32 m0, s32, 16
	s_add_i32 m0, m0, 0x10000
	v_mfma_f32_16x16x32_bf16 v[30:33], v[130:133], v[146:149], v[30:33]
	ds_read_b128 v[146:149], v227 offset:2048
	v_mfma_f32_16x16x32_bf16 v[38:41], v[142:145], v[200:203], v[38:41]
	v_mfma_f32_16x16x32_bf16 v[14:17], v[142:145], v[236:239], v[14:17]
	ds_read_b128 v[142:145], v226 offset:32768
	global_load_lds_dwordx4 v242, s[48:49]
	s_add_i32 m0, m0, 0x8000
	v_mfma_f32_16x16x32_bf16 v[26:29], v[138:141], v[200:203], v[26:29]
	v_mfma_f32_16x16x32_bf16 v[10:13], v[138:141], v[236:239], v[10:13]
	ds_read_b128 v[138:141], v226 offset:34816
	global_load_lds_dwordx4 v243, s[42:43]
	v_mfma_f32_16x16x32_bf16 v[22:25], v[134:137], v[200:203], v[22:25]
	v_mfma_f32_16x16x32_bf16 v[6:9], v[134:137], v[236:239], v[6:9]
	ds_read_b128 v[134:137], v226 offset:36864
	v_mfma_f32_16x16x32_bf16 v[18:21], v[130:133], v[200:203], v[18:21]
	ds_read_b128 v[200:203], v227 offset:4096
	v_mfma_f32_16x16x32_bf16 v[2:5], v[130:133], v[236:239], v[2:5]
	ds_read_b128 v[130:133], v226 offset:38912
	ds_read_b128 v[236:239], v227 offset:6144
	s_cmp_eq_u32 s14, s41
	s_mov_b32 s28, s41
	s_cbranch_scc0 .LBB0_639
.LBB0_640:
	s_and_b64 s[2:3], s[8:9], exec
	s_waitcnt vmcnt(0)
	v_readlane_b32 s2, v255, 15
	v_readlane_b32 s4, v255, 19
	v_readlane_b32 s3, v255, 16
	v_readlane_b32 s5, v255, 20
	s_cselect_b32 s42, s2, s4
	v_readlane_b32 s2, v255, 17
	s_cselect_b32 s28, s51, 0
	s_cselect_b32 s29, s52, 0
	s_cselect_b32 s43, s3, s5
	s_cselect_b32 s46, s2, 0
	s_cmp_lt_i32 s44, 4
	s_mov_b64 s[2:3], -1
	s_waitcnt vmcnt(0) lgkmcnt(0)
	s_barrier
	s_cbranch_scc1 .LBB0_1047
	s_cmp_lt_i32 s44, 6
	s_cbranch_scc1 .LBB0_1041
	s_cmp_gt_i32 s44, 6
	s_cbranch_scc0 .LBB0_654
	s_movk_i32 s15, 0x210
	v_lshlrev_b32_e32 v0, 3, v223
	v_mul_lo_u32 v132, v225, s15
	v_cvt_pk_bf16_f32 v131, v128, v129
	v_cvt_pk_bf16_f32 v130, v126, v127
	v_add3_u32 v0, v224, v132, v0
	v_cvt_pk_bf16_f32 v133, v124, v125
	v_cvt_pk_bf16_f32 v132, v122, v123
	ds_write2_b64 v0, v[130:131], v[132:133] offset1:4
	v_cvt_pk_bf16_f32 v131, v120, v121
	v_cvt_pk_bf16_f32 v130, v118, v119
	v_cvt_pk_bf16_f32 v133, v116, v117
	v_cvt_pk_bf16_f32 v132, v114, v115
	ds_write2_b64 v0, v[130:131], v[132:133] offset0:32 offset1:36
	v_cvt_pk_bf16_f32 v131, v112, v113
	v_cvt_pk_bf16_f32 v130, v110, v111
	v_cvt_pk_bf16_f32 v133, v108, v109
	v_cvt_pk_bf16_f32 v132, v106, v107
	v_add_u32_e32 v134, 0x2000, v0
	ds_write2_b64 v134, v[130:131], v[132:133] offset0:32 offset1:36
	v_cvt_pk_bf16_f32 v131, v104, v105
	v_cvt_pk_bf16_f32 v130, v102, v103
	v_cvt_pk_bf16_f32 v133, v100, v101
	v_cvt_pk_bf16_f32 v132, v98, v99
	ds_write2_b64 v134, v[130:131], v[132:133] offset0:64 offset1:68
	v_cvt_pk_bf16_f32 v131, v96, v97
	v_cvt_pk_bf16_f32 v130, v94, v95
	v_cvt_pk_bf16_f32 v133, v92, v93
	v_cvt_pk_bf16_f32 v132, v90, v91
	v_add_u32_e32 v134, 0x4000, v0
	ds_write2_b64 v134, v[130:131], v[132:133] offset0:64 offset1:68
	v_cvt_pk_bf16_f32 v131, v88, v89
	v_cvt_pk_bf16_f32 v130, v86, v87
	v_cvt_pk_bf16_f32 v133, v84, v85
	v_cvt_pk_bf16_f32 v132, v82, v83
	ds_write2_b64 v134, v[130:131], v[132:133] offset0:96 offset1:100
	v_cvt_pk_bf16_f32 v131, v80, v81
	v_cvt_pk_bf16_f32 v130, v78, v79
	v_cvt_pk_bf16_f32 v133, v76, v77
	v_cvt_pk_bf16_f32 v132, v74, v75
	v_add_u32_e32 v134, 0x6000, v0
	ds_write2_b64 v134, v[130:131], v[132:133] offset0:96 offset1:100
	v_cvt_pk_bf16_f32 v131, v72, v73
	v_cvt_pk_bf16_f32 v130, v70, v71
	v_cvt_pk_bf16_f32 v133, v68, v69
	v_cvt_pk_bf16_f32 v132, v66, v67
	ds_write2_b64 v134, v[130:131], v[132:133] offset0:128 offset1:132
	v_cvt_pk_bf16_f32 v131, v64, v65
	v_cvt_pk_bf16_f32 v130, v62, v63
	v_cvt_pk_bf16_f32 v133, v60, v61
	v_cvt_pk_bf16_f32 v132, v58, v59
	v_add_u32_e32 v134, 0x8000, v0
	ds_write2_b64 v134, v[130:131], v[132:133] offset0:128 offset1:132
	v_cvt_pk_bf16_f32 v131, v56, v57
	v_cvt_pk_bf16_f32 v130, v54, v55
	v_cvt_pk_bf16_f32 v133, v52, v53
	v_cvt_pk_bf16_f32 v132, v50, v51
	ds_write2_b64 v134, v[130:131], v[132:133] offset0:160 offset1:164
	v_cvt_pk_bf16_f32 v131, v48, v49
	v_cvt_pk_bf16_f32 v130, v46, v47
	v_cvt_pk_bf16_f32 v133, v44, v45
	v_cvt_pk_bf16_f32 v132, v42, v43
	v_add_u32_e32 v134, 0xa000, v0
	ds_write2_b64 v134, v[130:131], v[132:133] offset0:160 offset1:164
	v_cvt_pk_bf16_f32 v131, v36, v37
	v_cvt_pk_bf16_f32 v130, v34, v35
	v_cvt_pk_bf16_f32 v133, v32, v33
	v_cvt_pk_bf16_f32 v132, v30, v31
	ds_write2_b64 v134, v[130:131], v[132:133] offset0:192 offset1:196
	v_cvt_pk_bf16_f32 v131, v40, v41
	v_cvt_pk_bf16_f32 v130, v38, v39
	v_cvt_pk_bf16_f32 v133, v28, v29
	v_cvt_pk_bf16_f32 v132, v26, v27
	v_add_u32_e32 v134, 0xc000, v0
	ds_write2_b64 v134, v[130:131], v[132:133] offset0:192 offset1:196
	v_cvt_pk_bf16_f32 v131, v24, v25
	v_cvt_pk_bf16_f32 v130, v22, v23
	v_cvt_pk_bf16_f32 v133, v20, v21
	v_cvt_pk_bf16_f32 v132, v18, v19
	ds_write2_b64 v134, v[130:131], v[132:133] offset0:224 offset1:228
	v_cvt_pk_bf16_f32 v131, v16, v17
	v_cvt_pk_bf16_f32 v130, v14, v15
	v_cvt_pk_bf16_f32 v133, v12, v13
	v_cvt_pk_bf16_f32 v132, v10, v11
	v_add_u32_e32 v134, 0xe000, v0
	ds_write2_b64 v134, v[130:131], v[132:133] offset0:224 offset1:228
	v_cvt_pk_bf16_f32 v131, v8, v9
	v_cvt_pk_bf16_f32 v130, v6, v7
	v_cvt_pk_bf16_f32 v133, v4, v5
	v_cvt_pk_bf16_f32 v132, v2, v3
	v_add_u32_e32 v0, 0xe800, v0
	ds_write2_b64 v0, v[130:131], v[132:133] offset1:4
	v_lshlrev_b32_e32 v0, 2, v175
	v_and_b32_e32 v0, 0x7c, v0
	s_mul_i32 s2, s28, 0x10800
	v_readlane_b32 s48, v253, 61
	v_lshl_or_b32 v164, s47, 7, v0
	s_mul_hi_u32 s3, s28, 0x10800
	v_readlane_b32 s49, v253, 62
	s_add_u32 s2, s48, s2
	v_ashrrev_i32_e32 v165, 31, v164
	s_addc_u32 s3, s49, s3
	v_lshlrev_b64 v[130:131], 2, v[164:165]
	v_lshl_add_u64 v[150:151], s[2:3], 0, v[130:131]
	s_movk_i32 s2, 0x5000
	v_add_co_u32_e32 v134, vcc, s2, v150
	s_mov_b32 s2, 0xb000
	s_nop 0
	v_addc_co_u32_e32 v135, vcc, 0, v151, vcc
	v_add_co_u32_e32 v138, vcc, s2, v150
	v_readlane_b32 s50, v253, 63
	s_nop 0
	v_addc_co_u32_e32 v139, vcc, 0, v151, vcc
	v_add_co_u32_e32 v142, vcc, s25, v150
	s_mul_i32 s4, s28, 0x5800
	s_nop 0
	v_addc_co_u32_e32 v143, vcc, 0, v151, vcc
	s_mov_b32 s2, 0x8000
	v_readlane_b32 s51, v254, 0
	s_mul_hi_u32 s5, s28, 0x5800
	s_add_u32 s4, s50, s4
	v_add_co_u32_e32 v146, vcc, s2, v150
	s_addc_u32 s5, s51, s5
	s_nop 0
	v_addc_co_u32_e32 v147, vcc, 0, v151, vcc
	s_mov_b32 s2, 0xd000
	s_waitcnt lgkmcnt(0)
	s_barrier
	v_lshl_add_u64 v[158:159], s[4:5], 0, v[130:131]
	global_load_dwordx4 v[130:133], v[150:151], off
	v_add_co_u32_e32 v150, vcc, s2, v150
	global_load_dwordx4 v[134:137], v[134:135], off offset:2048
	s_nop 0
	global_load_dwordx4 v[138:141], v[138:139], off
	v_addc_co_u32_e32 v151, vcc, 0, v151, vcc
	global_load_dwordx4 v[142:145], v[142:143], off offset:3072
	s_nop 0
	global_load_dwordx4 v[146:149], v[146:147], off offset:1024
	s_nop 0
	global_load_dwordx4 v[150:153], v[150:151], off offset:3072
	s_nop 0
	global_load_dwordx4 v[154:157], v[158:159], off
	v_add_co_u32_e32 v158, vcc, 0x2000, v158
	v_ashrrev_i32_e32 v0, 5, v175
	s_nop 0
	v_addc_co_u32_e32 v159, vcc, 0, v159, vcc
	global_load_dwordx4 v[158:161], v[158:159], off offset:3072
	v_readlane_b32 s2, v252, 32
	v_readlane_b32 s3, v252, 33
	v_mul_lo_u32 v166, v0, s15
	v_and_b32_e32 v167, 31, v175
	s_mov_b32 s14, 0
	v_lshl_add_u64 v[164:165], v[164:165], 1, s[2:3]
	v_lshl_add_u32 v166, v167, 3, v166
	v_add_u32_e32 v167, s40, v0
	s_waitcnt vmcnt(0)
	s_mov_b32 s14, 0x8800
	v_mul_u32_u24_e32 v63, 0x2100, v0
	v_and_b32_e32 v64, 31, v175
	v_lshl_add_u32 v63, v64, 3, v63
	v_lshlrev_b32_e32 v61, 4, v0
	v_add_u32_e32 v61, 1, v61
	v_add_u32_e32 v62, s40, v61
	s_mov_b32 s4, 0x78787879
	v_mul_hi_i32 v60, v62, s4
	v_lshrrev_b32_e32 v64, 31, v60
	v_ashrrev_i32_e32 v60, 11, v60
	v_add_u32_e32 v60, v60, v64
	v_mul_i32_i24_e32 v60, 0x1100, v60
	v_sub_u32_e32 v60, v62, v60
	s_movk_i32 s4, 0x1600
	v_mad_i64_i32 v[58:59], s[4:5], v62, s4, v[164:165]
	v_mov_b32_e32 v56, 0x1600
	v_mov_b32_e32 v57, 0
	ds_read2_b64 v[26:29], v63 offset1:32
	ds_read2_b64 v[68:71], v63 offset0:66 offset1:98
	s_waitcnt lgkmcnt(0)
	v_lshlrev_b32_e32 v2, 16, v26
	v_and_b32_e32 v3, 0xffff0000, v26
	v_lshlrev_b32_e32 v4, 16, v27
	v_and_b32_e32 v5, 0xffff0000, v27
	v_lshlrev_b32_e32 v14, 16, v28
	v_and_b32_e32 v15, 0xffff0000, v28
	v_lshlrev_b32_e32 v16, 16, v29
	v_and_b32_e32 v17, 0xffff0000, v29
	v_lshlrev_b32_e32 v6, 16, v68
	v_and_b32_e32 v7, 0xffff0000, v68
	v_lshlrev_b32_e32 v8, 16, v69
	v_and_b32_e32 v9, 0xffff0000, v69
	v_lshlrev_b32_e32 v18, 16, v70
	v_and_b32_e32 v19, 0xffff0000, v70
	v_lshlrev_b32_e32 v20, 16, v71
	v_and_b32_e32 v21, 0xffff0000, v71
	v_add_u32_e32 v63, 0x420, v63
	v_add_u32_e32 v64, -1, v60
	v_add_u32_e32 v65, 0xfffffeff, v60
	v_cmp_gt_u32_e32 vcc, 0xfef, v65
	s_mov_b64 s[4:5], vcc
	v_cmp_gt_u32_e32 vcc, 0xef, v64
	s_or_b64 s[4:5], s[4:5], vcc
	v_add_u32_e32 v64, 15, v62
	v_cmp_gt_i32_e32 vcc, s14, v64
	s_and_b64 s[4:5], s[4:5], vcc
	s_xor_b64 s[4:5], s[4:5], exec
	s_cmp_eq_u64 s[4:5], 0
	s_cbranch_scc0 .Lconv_slow
	v_cmp_gt_u32_e32 vcc, 15, v0
	s_mov_b32 s6, 0xbfb8aa3b
	ds_read2_b64 v[26:29], v63 offset1:32
	s_waitcnt lgkmcnt(0)
	v_lshlrev_b32_e32 v10, 16, v26
	v_and_b32_e32 v11, 0xffff0000, v26
	v_lshlrev_b32_e32 v12, 16, v27
	v_and_b32_e32 v13, 0xffff0000, v27
	v_lshlrev_b32_e32 v22, 16, v28
	v_and_b32_e32 v23, 0xffff0000, v28
	v_lshlrev_b32_e32 v24, 16, v29
	v_and_b32_e32 v25, 0xffff0000, v29
	v_add_u32_e32 v63, 0x210, v63
	ds_read2_b64 v[26:29], v63 offset1:32
	v_pk_fma_f32 v[30:31], v[146:147], v[18:19], v[158:159]
	v_pk_fma_f32 v[32:33], v[148:149], v[20:21], v[160:161]
	v_pk_fma_f32 v[34:35], v[134:135], v[6:7], v[154:155]
	v_pk_fma_f32 v[36:37], v[136:137], v[8:9], v[156:157]
	v_pk_fma_f32 v[30:31], v[142:143], v[14:15], v[30:31]
	v_pk_fma_f32 v[32:33], v[144:145], v[16:17], v[32:33]
	v_pk_fma_f32 v[34:35], v[130:131], v[2:3], v[34:35]
	v_pk_fma_f32 v[36:37], v[132:133], v[4:5], v[36:37]
	v_pk_fma_f32 v[30:31], v[150:151], v[22:23], v[30:31]
	v_pk_fma_f32 v[32:33], v[152:153], v[24:25], v[32:33]
	v_pk_fma_f32 v[34:35], v[138:139], v[10:11], v[34:35]
	v_pk_fma_f32 v[36:37], v[140:141], v[12:13], v[36:37]
	v_pk_mul_f32 v[42:43], v[30:31], s[6:7] op_sel_hi:[1,0]
	v_pk_mul_f32 v[44:45], v[32:33], s[6:7] op_sel_hi:[1,0]
	v_exp_f32_e32 v42, v42
	v_exp_f32_e32 v43, v43
	v_exp_f32_e32 v44, v44
	v_exp_f32_e32 v45, v45
	v_pk_add_f32 v[42:43], v[42:43], 1.0 op_sel_hi:[1,0]
	v_pk_add_f32 v[44:45], v[44:45], 1.0 op_sel_hi:[1,0]
	v_rcp_f32_e32 v46, v42
	v_rcp_f32_e32 v47, v43
	v_rcp_f32_e32 v48, v44
	v_rcp_f32_e32 v49, v45
	v_pk_mul_f32 v[46:47], v[30:31], v[46:47]
	v_pk_mul_f32 v[48:49], v[32:33], v[48:49]
	v_pk_mul_f32 v[34:35], v[34:35], v[46:47]
	v_pk_mul_f32 v[36:37], v[36:37], v[48:49]
	v_cvt_pk_bf16_f32 v66, v34, v35
	v_cvt_pk_bf16_f32 v67, v36, v37
	global_store_dwordx2 v[58:59], v[66:67], off
	v_lshl_add_u64 v[58:59], v[58:59], 0, v[56:57]
	s_waitcnt lgkmcnt(0)
	v_lshlrev_b32_e32 v2, 16, v26
	v_and_b32_e32 v3, 0xffff0000, v26
	v_lshlrev_b32_e32 v4, 16, v27
	v_and_b32_e32 v5, 0xffff0000, v27
	v_lshlrev_b32_e32 v14, 16, v28
	v_and_b32_e32 v15, 0xffff0000, v28
	v_lshlrev_b32_e32 v16, 16, v29
	v_and_b32_e32 v17, 0xffff0000, v29
	v_add_u32_e32 v63, 0x210, v63
	ds_read2_b64 v[26:29], v63 offset1:32
	v_pk_fma_f32 v[30:31], v[146:147], v[22:23], v[158:159]
	v_pk_fma_f32 v[32:33], v[148:149], v[24:25], v[160:161]
	v_pk_fma_f32 v[34:35], v[134:135], v[10:11], v[154:155]
	v_pk_fma_f32 v[36:37], v[136:137], v[12:13], v[156:157]
	v_pk_fma_f32 v[30:31], v[142:143], v[18:19], v[30:31]
	v_pk_fma_f32 v[32:33], v[144:145], v[20:21], v[32:33]
	v_pk_fma_f32 v[34:35], v[130:131], v[6:7], v[34:35]
	v_pk_fma_f32 v[36:37], v[132:133], v[8:9], v[36:37]
	v_pk_fma_f32 v[30:31], v[150:151], v[14:15], v[30:31]
	v_pk_fma_f32 v[32:33], v[152:153], v[16:17], v[32:33]
	v_pk_fma_f32 v[34:35], v[138:139], v[2:3], v[34:35]
	v_pk_fma_f32 v[36:37], v[140:141], v[4:5], v[36:37]
	v_pk_mul_f32 v[42:43], v[30:31], s[6:7] op_sel_hi:[1,0]
	v_pk_mul_f32 v[44:45], v[32:33], s[6:7] op_sel_hi:[1,0]
	v_exp_f32_e32 v42, v42
	v_exp_f32_e32 v43, v43
	v_exp_f32_e32 v44, v44
	v_exp_f32_e32 v45, v45
	v_pk_add_f32 v[42:43], v[42:43], 1.0 op_sel_hi:[1,0]
	v_pk_add_f32 v[44:45], v[44:45], 1.0 op_sel_hi:[1,0]
	v_rcp_f32_e32 v46, v42
	v_rcp_f32_e32 v47, v43
	v_rcp_f32_e32 v48, v44
	v_rcp_f32_e32 v49, v45
	v_pk_mul_f32 v[46:47], v[30:31], v[46:47]
	v_pk_mul_f32 v[48:49], v[32:33], v[48:49]
	v_pk_mul_f32 v[34:35], v[34:35], v[46:47]
	v_pk_mul_f32 v[36:37], v[36:37], v[48:49]
	v_cvt_pk_bf16_f32 v66, v34, v35
	v_cvt_pk_bf16_f32 v67, v36, v37
	global_store_dwordx2 v[58:59], v[66:67], off
	v_lshl_add_u64 v[58:59], v[58:59], 0, v[56:57]
	s_waitcnt lgkmcnt(0)
	v_lshlrev_b32_e32 v6, 16, v26
	v_and_b32_e32 v7, 0xffff0000, v26
	v_lshlrev_b32_e32 v8, 16, v27
	v_and_b32_e32 v9, 0xffff0000, v27
	v_lshlrev_b32_e32 v18, 16, v28
	v_and_b32_e32 v19, 0xffff0000, v28
	v_lshlrev_b32_e32 v20, 16, v29
	v_and_b32_e32 v21, 0xffff0000, v29
	v_add_u32_e32 v63, 0x210, v63
	ds_read2_b64 v[26:29], v63 offset1:32
	v_pk_fma_f32 v[30:31], v[146:147], v[14:15], v[158:159]
	v_pk_fma_f32 v[32:33], v[148:149], v[16:17], v[160:161]
	v_pk_fma_f32 v[34:35], v[134:135], v[2:3], v[154:155]
	v_pk_fma_f32 v[36:37], v[136:137], v[4:5], v[156:157]
	v_pk_fma_f32 v[30:31], v[142:143], v[22:23], v[30:31]
	v_pk_fma_f32 v[32:33], v[144:145], v[24:25], v[32:33]
	v_pk_fma_f32 v[34:35], v[130:131], v[10:11], v[34:35]
	v_pk_fma_f32 v[36:37], v[132:133], v[12:13], v[36:37]
	v_pk_fma_f32 v[30:31], v[150:151], v[18:19], v[30:31]
	v_pk_fma_f32 v[32:33], v[152:153], v[20:21], v[32:33]
	v_pk_fma_f32 v[34:35], v[138:139], v[6:7], v[34:35]
	v_pk_fma_f32 v[36:37], v[140:141], v[8:9], v[36:37]
	v_pk_mul_f32 v[42:43], v[30:31], s[6:7] op_sel_hi:[1,0]
	v_pk_mul_f32 v[44:45], v[32:33], s[6:7] op_sel_hi:[1,0]
	v_exp_f32_e32 v42, v42
	v_exp_f32_e32 v43, v43
	v_exp_f32_e32 v44, v44
	v_exp_f32_e32 v45, v45
	v_pk_add_f32 v[42:43], v[42:43], 1.0 op_sel_hi:[1,0]
	v_pk_add_f32 v[44:45], v[44:45], 1.0 op_sel_hi:[1,0]
	v_rcp_f32_e32 v46, v42
	v_rcp_f32_e32 v47, v43
	v_rcp_f32_e32 v48, v44
	v_rcp_f32_e32 v49, v45
	v_pk_mul_f32 v[46:47], v[30:31], v[46:47]
	v_pk_mul_f32 v[48:49], v[32:33], v[48:49]
	v_pk_mul_f32 v[34:35], v[34:35], v[46:47]
	v_pk_mul_f32 v[36:37], v[36:37], v[48:49]
	v_cvt_pk_bf16_f32 v66, v34, v35
	v_cvt_pk_bf16_f32 v67, v36, v37
	global_store_dwordx2 v[58:59], v[66:67], off
	v_lshl_add_u64 v[58:59], v[58:59], 0, v[56:57]
	s_waitcnt lgkmcnt(0)
	v_lshlrev_b32_e32 v10, 16, v26
	v_and_b32_e32 v11, 0xffff0000, v26
	v_lshlrev_b32_e32 v12, 16, v27
	v_and_b32_e32 v13, 0xffff0000, v27
	v_lshlrev_b32_e32 v22, 16, v28
	v_and_b32_e32 v23, 0xffff0000, v28
	v_lshlrev_b32_e32 v24, 16, v29
	v_and_b32_e32 v25, 0xffff0000, v29
	v_add_u32_e32 v63, 0x210, v63
	ds_read2_b64 v[26:29], v63 offset1:32
	v_pk_fma_f32 v[30:31], v[146:147], v[18:19], v[158:159]
	v_pk_fma_f32 v[32:33], v[148:149], v[20:21], v[160:161]
	v_pk_fma_f32 v[34:35], v[134:135], v[6:7], v[154:155]
	v_pk_fma_f32 v[36:37], v[136:137], v[8:9], v[156:157]
	v_pk_fma_f32 v[30:31], v[142:143], v[14:15], v[30:31]
	v_pk_fma_f32 v[32:33], v[144:145], v[16:17], v[32:33]
	v_pk_fma_f32 v[34:35], v[130:131], v[2:3], v[34:35]
	v_pk_fma_f32 v[36:37], v[132:133], v[4:5], v[36:37]
	v_pk_fma_f32 v[30:31], v[150:151], v[22:23], v[30:31]
	v_pk_fma_f32 v[32:33], v[152:153], v[24:25], v[32:33]
	v_pk_fma_f32 v[34:35], v[138:139], v[10:11], v[34:35]
	v_pk_fma_f32 v[36:37], v[140:141], v[12:13], v[36:37]
	v_pk_mul_f32 v[42:43], v[30:31], s[6:7] op_sel_hi:[1,0]
	v_pk_mul_f32 v[44:45], v[32:33], s[6:7] op_sel_hi:[1,0]
	v_exp_f32_e32 v42, v42
	v_exp_f32_e32 v43, v43
	v_exp_f32_e32 v44, v44
	v_exp_f32_e32 v45, v45
	v_pk_add_f32 v[42:43], v[42:43], 1.0 op_sel_hi:[1,0]
	v_pk_add_f32 v[44:45], v[44:45], 1.0 op_sel_hi:[1,0]
	v_rcp_f32_e32 v46, v42
	v_rcp_f32_e32 v47, v43
	v_rcp_f32_e32 v48, v44
	v_rcp_f32_e32 v49, v45
	v_pk_mul_f32 v[46:47], v[30:31], v[46:47]
	v_pk_mul_f32 v[48:49], v[32:33], v[48:49]
	v_pk_mul_f32 v[34:35], v[34:35], v[46:47]
	v_pk_mul_f32 v[36:37], v[36:37], v[48:49]
	v_cvt_pk_bf16_f32 v66, v34, v35
	v_cvt_pk_bf16_f32 v67, v36, v37
	global_store_dwordx2 v[58:59], v[66:67], off
	v_lshl_add_u64 v[58:59], v[58:59], 0, v[56:57]
	s_waitcnt lgkmcnt(0)
	v_lshlrev_b32_e32 v2, 16, v26
	v_and_b32_e32 v3, 0xffff0000, v26
	v_lshlrev_b32_e32 v4, 16, v27
	v_and_b32_e32 v5, 0xffff0000, v27
	v_lshlrev_b32_e32 v14, 16, v28
	v_and_b32_e32 v15, 0xffff0000, v28
	v_lshlrev_b32_e32 v16, 16, v29
	v_and_b32_e32 v17, 0xffff0000, v29
	v_add_u32_e32 v63, 0x210, v63
	ds_read2_b64 v[26:29], v63 offset1:32
	v_pk_fma_f32 v[30:31], v[146:147], v[22:23], v[158:159]
	v_pk_fma_f32 v[32:33], v[148:149], v[24:25], v[160:161]
	v_pk_fma_f32 v[34:35], v[134:135], v[10:11], v[154:155]
	v_pk_fma_f32 v[36:37], v[136:137], v[12:13], v[156:157]
	v_pk_fma_f32 v[30:31], v[142:143], v[18:19], v[30:31]
	v_pk_fma_f32 v[32:33], v[144:145], v[20:21], v[32:33]
	v_pk_fma_f32 v[34:35], v[130:131], v[6:7], v[34:35]
	v_pk_fma_f32 v[36:37], v[132:133], v[8:9], v[36:37]
	v_pk_fma_f32 v[30:31], v[150:151], v[14:15], v[30:31]
	v_pk_fma_f32 v[32:33], v[152:153], v[16:17], v[32:33]
	v_pk_fma_f32 v[34:35], v[138:139], v[2:3], v[34:35]
	v_pk_fma_f32 v[36:37], v[140:141], v[4:5], v[36:37]
	v_pk_mul_f32 v[42:43], v[30:31], s[6:7] op_sel_hi:[1,0]
	v_pk_mul_f32 v[44:45], v[32:33], s[6:7] op_sel_hi:[1,0]
	v_exp_f32_e32 v42, v42
	v_exp_f32_e32 v43, v43
	v_exp_f32_e32 v44, v44
	v_exp_f32_e32 v45, v45
	v_pk_add_f32 v[42:43], v[42:43], 1.0 op_sel_hi:[1,0]
	v_pk_add_f32 v[44:45], v[44:45], 1.0 op_sel_hi:[1,0]
	v_rcp_f32_e32 v46, v42
	v_rcp_f32_e32 v47, v43
	v_rcp_f32_e32 v48, v44
	v_rcp_f32_e32 v49, v45
	v_pk_mul_f32 v[46:47], v[30:31], v[46:47]
	v_pk_mul_f32 v[48:49], v[32:33], v[48:49]
	v_pk_mul_f32 v[34:35], v[34:35], v[46:47]
	v_pk_mul_f32 v[36:37], v[36:37], v[48:49]
	v_cvt_pk_bf16_f32 v66, v34, v35
	v_cvt_pk_bf16_f32 v67, v36, v37
	global_store_dwordx2 v[58:59], v[66:67], off
	v_lshl_add_u64 v[58:59], v[58:59], 0, v[56:57]
	s_waitcnt lgkmcnt(0)
	v_lshlrev_b32_e32 v6, 16, v26
	v_and_b32_e32 v7, 0xffff0000, v26
	v_lshlrev_b32_e32 v8, 16, v27
	v_and_b32_e32 v9, 0xffff0000, v27
	v_lshlrev_b32_e32 v18, 16, v28
	v_and_b32_e32 v19, 0xffff0000, v28
	v_lshlrev_b32_e32 v20, 16, v29
	v_and_b32_e32 v21, 0xffff0000, v29
	v_add_u32_e32 v63, 0x210, v63
	ds_read2_b64 v[26:29], v63 offset1:32
	v_pk_fma_f32 v[30:31], v[146:147], v[14:15], v[158:159]
	v_pk_fma_f32 v[32:33], v[148:149], v[16:17], v[160:161]
	v_pk_fma_f32 v[34:35], v[134:135], v[2:3], v[154:155]
	v_pk_fma_f32 v[36:37], v[136:137], v[4:5], v[156:157]
	v_pk_fma_f32 v[30:31], v[142:143], v[22:23], v[30:31]
	v_pk_fma_f32 v[32:33], v[144:145], v[24:25], v[32:33]
	v_pk_fma_f32 v[34:35], v[130:131], v[10:11], v[34:35]
	v_pk_fma_f32 v[36:37], v[132:133], v[12:13], v[36:37]
	v_pk_fma_f32 v[30:31], v[150:151], v[18:19], v[30:31]
	v_pk_fma_f32 v[32:33], v[152:153], v[20:21], v[32:33]
	v_pk_fma_f32 v[34:35], v[138:139], v[6:7], v[34:35]
	v_pk_fma_f32 v[36:37], v[140:141], v[8:9], v[36:37]
	v_pk_mul_f32 v[42:43], v[30:31], s[6:7] op_sel_hi:[1,0]
	v_pk_mul_f32 v[44:45], v[32:33], s[6:7] op_sel_hi:[1,0]
	v_exp_f32_e32 v42, v42
	v_exp_f32_e32 v43, v43
	v_exp_f32_e32 v44, v44
	v_exp_f32_e32 v45, v45
	v_pk_add_f32 v[42:43], v[42:43], 1.0 op_sel_hi:[1,0]
	v_pk_add_f32 v[44:45], v[44:45], 1.0 op_sel_hi:[1,0]
	v_rcp_f32_e32 v46, v42
	v_rcp_f32_e32 v47, v43
	v_rcp_f32_e32 v48, v44
	v_rcp_f32_e32 v49, v45
	v_pk_mul_f32 v[46:47], v[30:31], v[46:47]
	v_pk_mul_f32 v[48:49], v[32:33], v[48:49]
	v_pk_mul_f32 v[34:35], v[34:35], v[46:47]
	v_pk_mul_f32 v[36:37], v[36:37], v[48:49]
	v_cvt_pk_bf16_f32 v66, v34, v35
	v_cvt_pk_bf16_f32 v67, v36, v37
	global_store_dwordx2 v[58:59], v[66:67], off
	v_lshl_add_u64 v[58:59], v[58:59], 0, v[56:57]
	s_waitcnt lgkmcnt(0)
	v_lshlrev_b32_e32 v10, 16, v26
	v_and_b32_e32 v11, 0xffff0000, v26
	v_lshlrev_b32_e32 v12, 16, v27
	v_and_b32_e32 v13, 0xffff0000, v27
	v_lshlrev_b32_e32 v22, 16, v28
	v_and_b32_e32 v23, 0xffff0000, v28
	v_lshlrev_b32_e32 v24, 16, v29
	v_and_b32_e32 v25, 0xffff0000, v29
	v_add_u32_e32 v63, 0x210, v63
	ds_read2_b64 v[26:29], v63 offset1:32
	v_pk_fma_f32 v[30:31], v[146:147], v[18:19], v[158:159]
	v_pk_fma_f32 v[32:33], v[148:149], v[20:21], v[160:161]
	v_pk_fma_f32 v[34:35], v[134:135], v[6:7], v[154:155]
	v_pk_fma_f32 v[36:37], v[136:137], v[8:9], v[156:157]
	v_pk_fma_f32 v[30:31], v[142:143], v[14:15], v[30:31]
	v_pk_fma_f32 v[32:33], v[144:145], v[16:17], v[32:33]
	v_pk_fma_f32 v[34:35], v[130:131], v[2:3], v[34:35]
	v_pk_fma_f32 v[36:37], v[132:133], v[4:5], v[36:37]
	v_pk_fma_f32 v[30:31], v[150:151], v[22:23], v[30:31]
	v_pk_fma_f32 v[32:33], v[152:153], v[24:25], v[32:33]
	v_pk_fma_f32 v[34:35], v[138:139], v[10:11], v[34:35]
	v_pk_fma_f32 v[36:37], v[140:141], v[12:13], v[36:37]
	v_pk_mul_f32 v[42:43], v[30:31], s[6:7] op_sel_hi:[1,0]
	v_pk_mul_f32 v[44:45], v[32:33], s[6:7] op_sel_hi:[1,0]
	v_exp_f32_e32 v42, v42
	v_exp_f32_e32 v43, v43
	v_exp_f32_e32 v44, v44
	v_exp_f32_e32 v45, v45
	v_pk_add_f32 v[42:43], v[42:43], 1.0 op_sel_hi:[1,0]
	v_pk_add_f32 v[44:45], v[44:45], 1.0 op_sel_hi:[1,0]
	v_rcp_f32_e32 v46, v42
	v_rcp_f32_e32 v47, v43
	v_rcp_f32_e32 v48, v44
	v_rcp_f32_e32 v49, v45
	v_pk_mul_f32 v[46:47], v[30:31], v[46:47]
	v_pk_mul_f32 v[48:49], v[32:33], v[48:49]
	v_pk_mul_f32 v[34:35], v[34:35], v[46:47]
	v_pk_mul_f32 v[36:37], v[36:37], v[48:49]
	v_cvt_pk_bf16_f32 v66, v34, v35
	v_cvt_pk_bf16_f32 v67, v36, v37
	global_store_dwordx2 v[58:59], v[66:67], off
	v_lshl_add_u64 v[58:59], v[58:59], 0, v[56:57]
	s_waitcnt lgkmcnt(0)
	v_lshlrev_b32_e32 v2, 16, v26
	v_and_b32_e32 v3, 0xffff0000, v26
	v_lshlrev_b32_e32 v4, 16, v27
	v_and_b32_e32 v5, 0xffff0000, v27
	v_lshlrev_b32_e32 v14, 16, v28
	v_and_b32_e32 v15, 0xffff0000, v28
	v_lshlrev_b32_e32 v16, 16, v29
	v_and_b32_e32 v17, 0xffff0000, v29
	v_add_u32_e32 v63, 0x210, v63
	ds_read2_b64 v[26:29], v63 offset1:32
	v_pk_fma_f32 v[30:31], v[146:147], v[22:23], v[158:159]
	v_pk_fma_f32 v[32:33], v[148:149], v[24:25], v[160:161]
	v_pk_fma_f32 v[34:35], v[134:135], v[10:11], v[154:155]
	v_pk_fma_f32 v[36:37], v[136:137], v[12:13], v[156:157]
	v_pk_fma_f32 v[30:31], v[142:143], v[18:19], v[30:31]
	v_pk_fma_f32 v[32:33], v[144:145], v[20:21], v[32:33]
	v_pk_fma_f32 v[34:35], v[130:131], v[6:7], v[34:35]
	v_pk_fma_f32 v[36:37], v[132:133], v[8:9], v[36:37]
	v_pk_fma_f32 v[30:31], v[150:151], v[14:15], v[30:31]
	v_pk_fma_f32 v[32:33], v[152:153], v[16:17], v[32:33]
	v_pk_fma_f32 v[34:35], v[138:139], v[2:3], v[34:35]
	v_pk_fma_f32 v[36:37], v[140:141], v[4:5], v[36:37]
	v_pk_mul_f32 v[42:43], v[30:31], s[6:7] op_sel_hi:[1,0]
	v_pk_mul_f32 v[44:45], v[32:33], s[6:7] op_sel_hi:[1,0]
	v_exp_f32_e32 v42, v42
	v_exp_f32_e32 v43, v43
	v_exp_f32_e32 v44, v44
	v_exp_f32_e32 v45, v45
	v_pk_add_f32 v[42:43], v[42:43], 1.0 op_sel_hi:[1,0]
	v_pk_add_f32 v[44:45], v[44:45], 1.0 op_sel_hi:[1,0]
	v_rcp_f32_e32 v46, v42
	v_rcp_f32_e32 v47, v43
	v_rcp_f32_e32 v48, v44
	v_rcp_f32_e32 v49, v45
	v_pk_mul_f32 v[46:47], v[30:31], v[46:47]
	v_pk_mul_f32 v[48:49], v[32:33], v[48:49]
	v_pk_mul_f32 v[34:35], v[34:35], v[46:47]
	v_pk_mul_f32 v[36:37], v[36:37], v[48:49]
	v_cvt_pk_bf16_f32 v66, v34, v35
	v_cvt_pk_bf16_f32 v67, v36, v37
	global_store_dwordx2 v[58:59], v[66:67], off
	v_lshl_add_u64 v[58:59], v[58:59], 0, v[56:57]
	s_waitcnt lgkmcnt(0)
	v_lshlrev_b32_e32 v6, 16, v26
	v_and_b32_e32 v7, 0xffff0000, v26
	v_lshlrev_b32_e32 v8, 16, v27
	v_and_b32_e32 v9, 0xffff0000, v27
	v_lshlrev_b32_e32 v18, 16, v28
	v_and_b32_e32 v19, 0xffff0000, v28
	v_lshlrev_b32_e32 v20, 16, v29
	v_and_b32_e32 v21, 0xffff0000, v29
	v_add_u32_e32 v63, 0x210, v63
	ds_read2_b64 v[26:29], v63 offset1:32
	v_pk_fma_f32 v[30:31], v[146:147], v[14:15], v[158:159]
	v_pk_fma_f32 v[32:33], v[148:149], v[16:17], v[160:161]
	v_pk_fma_f32 v[34:35], v[134:135], v[2:3], v[154:155]
	v_pk_fma_f32 v[36:37], v[136:137], v[4:5], v[156:157]
	v_pk_fma_f32 v[30:31], v[142:143], v[22:23], v[30:31]
	v_pk_fma_f32 v[32:33], v[144:145], v[24:25], v[32:33]
	v_pk_fma_f32 v[34:35], v[130:131], v[10:11], v[34:35]
	v_pk_fma_f32 v[36:37], v[132:133], v[12:13], v[36:37]
	v_pk_fma_f32 v[30:31], v[150:151], v[18:19], v[30:31]
	v_pk_fma_f32 v[32:33], v[152:153], v[20:21], v[32:33]
	v_pk_fma_f32 v[34:35], v[138:139], v[6:7], v[34:35]
	v_pk_fma_f32 v[36:37], v[140:141], v[8:9], v[36:37]
	v_pk_mul_f32 v[42:43], v[30:31], s[6:7] op_sel_hi:[1,0]
	v_pk_mul_f32 v[44:45], v[32:33], s[6:7] op_sel_hi:[1,0]
	v_exp_f32_e32 v42, v42
	v_exp_f32_e32 v43, v43
	v_exp_f32_e32 v44, v44
	v_exp_f32_e32 v45, v45
	v_pk_add_f32 v[42:43], v[42:43], 1.0 op_sel_hi:[1,0]
	v_pk_add_f32 v[44:45], v[44:45], 1.0 op_sel_hi:[1,0]
	v_rcp_f32_e32 v46, v42
	v_rcp_f32_e32 v47, v43
	v_rcp_f32_e32 v48, v44
	v_rcp_f32_e32 v49, v45
	v_pk_mul_f32 v[46:47], v[30:31], v[46:47]
	v_pk_mul_f32 v[48:49], v[32:33], v[48:49]
	v_pk_mul_f32 v[34:35], v[34:35], v[46:47]
	v_pk_mul_f32 v[36:37], v[36:37], v[48:49]
	v_cvt_pk_bf16_f32 v66, v34, v35
	v_cvt_pk_bf16_f32 v67, v36, v37
	global_store_dwordx2 v[58:59], v[66:67], off
	v_lshl_add_u64 v[58:59], v[58:59], 0, v[56:57]
	s_waitcnt lgkmcnt(0)
	v_lshlrev_b32_e32 v10, 16, v26
	v_and_b32_e32 v11, 0xffff0000, v26
	v_lshlrev_b32_e32 v12, 16, v27
	v_and_b32_e32 v13, 0xffff0000, v27
	v_lshlrev_b32_e32 v22, 16, v28
	v_and_b32_e32 v23, 0xffff0000, v28
	v_lshlrev_b32_e32 v24, 16, v29
	v_and_b32_e32 v25, 0xffff0000, v29
	v_add_u32_e32 v63, 0x210, v63
	ds_read2_b64 v[26:29], v63 offset1:32
	v_pk_fma_f32 v[30:31], v[146:147], v[18:19], v[158:159]
	v_pk_fma_f32 v[32:33], v[148:149], v[20:21], v[160:161]
	v_pk_fma_f32 v[34:35], v[134:135], v[6:7], v[154:155]
	v_pk_fma_f32 v[36:37], v[136:137], v[8:9], v[156:157]
	v_pk_fma_f32 v[30:31], v[142:143], v[14:15], v[30:31]
	v_pk_fma_f32 v[32:33], v[144:145], v[16:17], v[32:33]
	v_pk_fma_f32 v[34:35], v[130:131], v[2:3], v[34:35]
	v_pk_fma_f32 v[36:37], v[132:133], v[4:5], v[36:37]
	v_pk_fma_f32 v[30:31], v[150:151], v[22:23], v[30:31]
	v_pk_fma_f32 v[32:33], v[152:153], v[24:25], v[32:33]
	v_pk_fma_f32 v[34:35], v[138:139], v[10:11], v[34:35]
	v_pk_fma_f32 v[36:37], v[140:141], v[12:13], v[36:37]
	v_pk_mul_f32 v[42:43], v[30:31], s[6:7] op_sel_hi:[1,0]
	v_pk_mul_f32 v[44:45], v[32:33], s[6:7] op_sel_hi:[1,0]
	v_exp_f32_e32 v42, v42
	v_exp_f32_e32 v43, v43
	v_exp_f32_e32 v44, v44
	v_exp_f32_e32 v45, v45
	v_pk_add_f32 v[42:43], v[42:43], 1.0 op_sel_hi:[1,0]
	v_pk_add_f32 v[44:45], v[44:45], 1.0 op_sel_hi:[1,0]
	v_rcp_f32_e32 v46, v42
	v_rcp_f32_e32 v47, v43
	v_rcp_f32_e32 v48, v44
	v_rcp_f32_e32 v49, v45
	v_pk_mul_f32 v[46:47], v[30:31], v[46:47]
	v_pk_mul_f32 v[48:49], v[32:33], v[48:49]
	v_pk_mul_f32 v[34:35], v[34:35], v[46:47]
	v_pk_mul_f32 v[36:37], v[36:37], v[48:49]
	v_cvt_pk_bf16_f32 v66, v34, v35
	v_cvt_pk_bf16_f32 v67, v36, v37
	global_store_dwordx2 v[58:59], v[66:67], off
	v_lshl_add_u64 v[58:59], v[58:59], 0, v[56:57]
	s_waitcnt lgkmcnt(0)
	v_lshlrev_b32_e32 v2, 16, v26
	v_and_b32_e32 v3, 0xffff0000, v26
	v_lshlrev_b32_e32 v4, 16, v27
	v_and_b32_e32 v5, 0xffff0000, v27
	v_lshlrev_b32_e32 v14, 16, v28
	v_and_b32_e32 v15, 0xffff0000, v28
	v_lshlrev_b32_e32 v16, 16, v29
	v_and_b32_e32 v17, 0xffff0000, v29
	v_add_u32_e32 v63, 0x210, v63
	ds_read2_b64 v[26:29], v63 offset1:32
	v_pk_fma_f32 v[30:31], v[146:147], v[22:23], v[158:159]
	v_pk_fma_f32 v[32:33], v[148:149], v[24:25], v[160:161]
	v_pk_fma_f32 v[34:35], v[134:135], v[10:11], v[154:155]
	v_pk_fma_f32 v[36:37], v[136:137], v[12:13], v[156:157]
	v_pk_fma_f32 v[30:31], v[142:143], v[18:19], v[30:31]
	v_pk_fma_f32 v[32:33], v[144:145], v[20:21], v[32:33]
	v_pk_fma_f32 v[34:35], v[130:131], v[6:7], v[34:35]
	v_pk_fma_f32 v[36:37], v[132:133], v[8:9], v[36:37]
	v_pk_fma_f32 v[30:31], v[150:151], v[14:15], v[30:31]
	v_pk_fma_f32 v[32:33], v[152:153], v[16:17], v[32:33]
	v_pk_fma_f32 v[34:35], v[138:139], v[2:3], v[34:35]
	v_pk_fma_f32 v[36:37], v[140:141], v[4:5], v[36:37]
	v_pk_mul_f32 v[42:43], v[30:31], s[6:7] op_sel_hi:[1,0]
	v_pk_mul_f32 v[44:45], v[32:33], s[6:7] op_sel_hi:[1,0]
	v_exp_f32_e32 v42, v42
	v_exp_f32_e32 v43, v43
	v_exp_f32_e32 v44, v44
	v_exp_f32_e32 v45, v45
	v_pk_add_f32 v[42:43], v[42:43], 1.0 op_sel_hi:[1,0]
	v_pk_add_f32 v[44:45], v[44:45], 1.0 op_sel_hi:[1,0]
	v_rcp_f32_e32 v46, v42
	v_rcp_f32_e32 v47, v43
	v_rcp_f32_e32 v48, v44
	v_rcp_f32_e32 v49, v45
	v_pk_mul_f32 v[46:47], v[30:31], v[46:47]
	v_pk_mul_f32 v[48:49], v[32:33], v[48:49]
	v_pk_mul_f32 v[34:35], v[34:35], v[46:47]
	v_pk_mul_f32 v[36:37], v[36:37], v[48:49]
	v_cvt_pk_bf16_f32 v66, v34, v35
	v_cvt_pk_bf16_f32 v67, v36, v37
	global_store_dwordx2 v[58:59], v[66:67], off
	v_lshl_add_u64 v[58:59], v[58:59], 0, v[56:57]
	s_waitcnt lgkmcnt(0)
	v_lshlrev_b32_e32 v6, 16, v26
	v_and_b32_e32 v7, 0xffff0000, v26
	v_lshlrev_b32_e32 v8, 16, v27
	v_and_b32_e32 v9, 0xffff0000, v27
	v_lshlrev_b32_e32 v18, 16, v28
	v_and_b32_e32 v19, 0xffff0000, v28
	v_lshlrev_b32_e32 v20, 16, v29
	v_and_b32_e32 v21, 0xffff0000, v29
	v_add_u32_e32 v63, 0x210, v63
	ds_read2_b64 v[26:29], v63 offset1:32
	v_pk_fma_f32 v[30:31], v[146:147], v[14:15], v[158:159]
	v_pk_fma_f32 v[32:33], v[148:149], v[16:17], v[160:161]
	v_pk_fma_f32 v[34:35], v[134:135], v[2:3], v[154:155]
	v_pk_fma_f32 v[36:37], v[136:137], v[4:5], v[156:157]
	v_pk_fma_f32 v[30:31], v[142:143], v[22:23], v[30:31]
	v_pk_fma_f32 v[32:33], v[144:145], v[24:25], v[32:33]
	v_pk_fma_f32 v[34:35], v[130:131], v[10:11], v[34:35]
	v_pk_fma_f32 v[36:37], v[132:133], v[12:13], v[36:37]
	v_pk_fma_f32 v[30:31], v[150:151], v[18:19], v[30:31]
	v_pk_fma_f32 v[32:33], v[152:153], v[20:21], v[32:33]
	v_pk_fma_f32 v[34:35], v[138:139], v[6:7], v[34:35]
	v_pk_fma_f32 v[36:37], v[140:141], v[8:9], v[36:37]
	v_pk_mul_f32 v[42:43], v[30:31], s[6:7] op_sel_hi:[1,0]
	v_pk_mul_f32 v[44:45], v[32:33], s[6:7] op_sel_hi:[1,0]
	v_exp_f32_e32 v42, v42
	v_exp_f32_e32 v43, v43
	v_exp_f32_e32 v44, v44
	v_exp_f32_e32 v45, v45
	v_pk_add_f32 v[42:43], v[42:43], 1.0 op_sel_hi:[1,0]
	v_pk_add_f32 v[44:45], v[44:45], 1.0 op_sel_hi:[1,0]
	v_rcp_f32_e32 v46, v42
	v_rcp_f32_e32 v47, v43
	v_rcp_f32_e32 v48, v44
	v_rcp_f32_e32 v49, v45
	v_pk_mul_f32 v[46:47], v[30:31], v[46:47]
	v_pk_mul_f32 v[48:49], v[32:33], v[48:49]
	v_pk_mul_f32 v[34:35], v[34:35], v[46:47]
	v_pk_mul_f32 v[36:37], v[36:37], v[48:49]
	v_cvt_pk_bf16_f32 v66, v34, v35
	v_cvt_pk_bf16_f32 v67, v36, v37
	global_store_dwordx2 v[58:59], v[66:67], off
	v_lshl_add_u64 v[58:59], v[58:59], 0, v[56:57]
	s_waitcnt lgkmcnt(0)
	v_lshlrev_b32_e32 v10, 16, v26
	v_and_b32_e32 v11, 0xffff0000, v26
	v_lshlrev_b32_e32 v12, 16, v27
	v_and_b32_e32 v13, 0xffff0000, v27
	v_lshlrev_b32_e32 v22, 16, v28
	v_and_b32_e32 v23, 0xffff0000, v28
	v_lshlrev_b32_e32 v24, 16, v29
	v_and_b32_e32 v25, 0xffff0000, v29
	v_add_u32_e32 v63, 0x210, v63
	ds_read2_b64 v[26:29], v63 offset1:32
	v_pk_fma_f32 v[30:31], v[146:147], v[18:19], v[158:159]
	v_pk_fma_f32 v[32:33], v[148:149], v[20:21], v[160:161]
	v_pk_fma_f32 v[34:35], v[134:135], v[6:7], v[154:155]
	v_pk_fma_f32 v[36:37], v[136:137], v[8:9], v[156:157]
	v_pk_fma_f32 v[30:31], v[142:143], v[14:15], v[30:31]
	v_pk_fma_f32 v[32:33], v[144:145], v[16:17], v[32:33]
	v_pk_fma_f32 v[34:35], v[130:131], v[2:3], v[34:35]
	v_pk_fma_f32 v[36:37], v[132:133], v[4:5], v[36:37]
	v_pk_fma_f32 v[30:31], v[150:151], v[22:23], v[30:31]
	v_pk_fma_f32 v[32:33], v[152:153], v[24:25], v[32:33]
	v_pk_fma_f32 v[34:35], v[138:139], v[10:11], v[34:35]
	v_pk_fma_f32 v[36:37], v[140:141], v[12:13], v[36:37]
	v_pk_mul_f32 v[42:43], v[30:31], s[6:7] op_sel_hi:[1,0]
	v_pk_mul_f32 v[44:45], v[32:33], s[6:7] op_sel_hi:[1,0]
	v_exp_f32_e32 v42, v42
	v_exp_f32_e32 v43, v43
	v_exp_f32_e32 v44, v44
	v_exp_f32_e32 v45, v45
	v_pk_add_f32 v[42:43], v[42:43], 1.0 op_sel_hi:[1,0]
	v_pk_add_f32 v[44:45], v[44:45], 1.0 op_sel_hi:[1,0]
	v_rcp_f32_e32 v46, v42
	v_rcp_f32_e32 v47, v43
	v_rcp_f32_e32 v48, v44
	v_rcp_f32_e32 v49, v45
	v_pk_mul_f32 v[46:47], v[30:31], v[46:47]
	v_pk_mul_f32 v[48:49], v[32:33], v[48:49]
	v_pk_mul_f32 v[34:35], v[34:35], v[46:47]
	v_pk_mul_f32 v[36:37], v[36:37], v[48:49]
	v_cvt_pk_bf16_f32 v66, v34, v35
	v_cvt_pk_bf16_f32 v67, v36, v37
	global_store_dwordx2 v[58:59], v[66:67], off
	v_lshl_add_u64 v[58:59], v[58:59], 0, v[56:57]
	s_waitcnt lgkmcnt(0)
	v_lshlrev_b32_e32 v2, 16, v26
	v_and_b32_e32 v3, 0xffff0000, v26
	v_lshlrev_b32_e32 v4, 16, v27
	v_and_b32_e32 v5, 0xffff0000, v27
	v_lshlrev_b32_e32 v14, 16, v28
	v_and_b32_e32 v15, 0xffff0000, v28
	v_lshlrev_b32_e32 v16, 16, v29
	v_and_b32_e32 v17, 0xffff0000, v29
	v_add_u32_e32 v63, 0x210, v63
	ds_read2_b64 v[26:29], v63 offset1:32
	v_pk_fma_f32 v[30:31], v[146:147], v[22:23], v[158:159]
	v_pk_fma_f32 v[32:33], v[148:149], v[24:25], v[160:161]
	v_pk_fma_f32 v[34:35], v[134:135], v[10:11], v[154:155]
	v_pk_fma_f32 v[36:37], v[136:137], v[12:13], v[156:157]
	v_pk_fma_f32 v[30:31], v[142:143], v[18:19], v[30:31]
	v_pk_fma_f32 v[32:33], v[144:145], v[20:21], v[32:33]
	v_pk_fma_f32 v[34:35], v[130:131], v[6:7], v[34:35]
	v_pk_fma_f32 v[36:37], v[132:133], v[8:9], v[36:37]
	v_pk_fma_f32 v[30:31], v[150:151], v[14:15], v[30:31]
	v_pk_fma_f32 v[32:33], v[152:153], v[16:17], v[32:33]
	v_pk_fma_f32 v[34:35], v[138:139], v[2:3], v[34:35]
	v_pk_fma_f32 v[36:37], v[140:141], v[4:5], v[36:37]
	v_pk_mul_f32 v[42:43], v[30:31], s[6:7] op_sel_hi:[1,0]
	v_pk_mul_f32 v[44:45], v[32:33], s[6:7] op_sel_hi:[1,0]
	v_exp_f32_e32 v42, v42
	v_exp_f32_e32 v43, v43
	v_exp_f32_e32 v44, v44
	v_exp_f32_e32 v45, v45
	v_pk_add_f32 v[42:43], v[42:43], 1.0 op_sel_hi:[1,0]
	v_pk_add_f32 v[44:45], v[44:45], 1.0 op_sel_hi:[1,0]
	v_rcp_f32_e32 v46, v42
	v_rcp_f32_e32 v47, v43
	v_rcp_f32_e32 v48, v44
	v_rcp_f32_e32 v49, v45
	v_pk_mul_f32 v[46:47], v[30:31], v[46:47]
	v_pk_mul_f32 v[48:49], v[32:33], v[48:49]
	v_pk_mul_f32 v[34:35], v[34:35], v[46:47]
	v_pk_mul_f32 v[36:37], v[36:37], v[48:49]
	v_cvt_pk_bf16_f32 v66, v34, v35
	v_cvt_pk_bf16_f32 v67, v36, v37
	global_store_dwordx2 v[58:59], v[66:67], off
	v_lshl_add_u64 v[58:59], v[58:59], 0, v[56:57]
	s_waitcnt lgkmcnt(0)
	v_lshlrev_b32_e32 v6, 16, v26
	v_and_b32_e32 v7, 0xffff0000, v26
	v_lshlrev_b32_e32 v8, 16, v27
	v_and_b32_e32 v9, 0xffff0000, v27
	v_lshlrev_b32_e32 v18, 16, v28
	v_and_b32_e32 v19, 0xffff0000, v28
	v_lshlrev_b32_e32 v20, 16, v29
	v_and_b32_e32 v21, 0xffff0000, v29
	v_add_u32_e32 v63, 0x210, v63
	ds_read2_b64 v[26:29], v63 offset1:32
	v_pk_fma_f32 v[30:31], v[146:147], v[14:15], v[158:159]
	v_pk_fma_f32 v[32:33], v[148:149], v[16:17], v[160:161]
	v_pk_fma_f32 v[34:35], v[134:135], v[2:3], v[154:155]
	v_pk_fma_f32 v[36:37], v[136:137], v[4:5], v[156:157]
	v_pk_fma_f32 v[30:31], v[142:143], v[22:23], v[30:31]
	v_pk_fma_f32 v[32:33], v[144:145], v[24:25], v[32:33]
	v_pk_fma_f32 v[34:35], v[130:131], v[10:11], v[34:35]
	v_pk_fma_f32 v[36:37], v[132:133], v[12:13], v[36:37]
	v_pk_fma_f32 v[30:31], v[150:151], v[18:19], v[30:31]
	v_pk_fma_f32 v[32:33], v[152:153], v[20:21], v[32:33]
	v_pk_fma_f32 v[34:35], v[138:139], v[6:7], v[34:35]
	v_pk_fma_f32 v[36:37], v[140:141], v[8:9], v[36:37]
	v_pk_mul_f32 v[42:43], v[30:31], s[6:7] op_sel_hi:[1,0]
	v_pk_mul_f32 v[44:45], v[32:33], s[6:7] op_sel_hi:[1,0]
	v_exp_f32_e32 v42, v42
	v_exp_f32_e32 v43, v43
	v_exp_f32_e32 v44, v44
	v_exp_f32_e32 v45, v45
	v_pk_add_f32 v[42:43], v[42:43], 1.0 op_sel_hi:[1,0]
	v_pk_add_f32 v[44:45], v[44:45], 1.0 op_sel_hi:[1,0]
	v_rcp_f32_e32 v46, v42
	v_rcp_f32_e32 v47, v43
	v_rcp_f32_e32 v48, v44
	v_rcp_f32_e32 v49, v45
	v_pk_mul_f32 v[46:47], v[30:31], v[46:47]
	v_pk_mul_f32 v[48:49], v[32:33], v[48:49]
	v_pk_mul_f32 v[34:35], v[34:35], v[46:47]
	v_pk_mul_f32 v[36:37], v[36:37], v[48:49]
	v_cvt_pk_bf16_f32 v66, v34, v35
	v_cvt_pk_bf16_f32 v67, v36, v37
	s_and_saveexec_b64 s[4:5], vcc
	global_store_dwordx2 v[58:59], v[66:67], off
	s_or_b64 exec, exec, s[4:5]
	v_lshl_add_u64 v[58:59], v[58:59], 0, v[56:57]
	s_waitcnt lgkmcnt(0)
	v_lshlrev_b32_e32 v10, 16, v26
	v_and_b32_e32 v11, 0xffff0000, v26
	v_lshlrev_b32_e32 v12, 16, v27
	v_and_b32_e32 v13, 0xffff0000, v27
	v_lshlrev_b32_e32 v22, 16, v28
	v_and_b32_e32 v23, 0xffff0000, v28
	v_lshlrev_b32_e32 v24, 16, v29
	v_and_b32_e32 v25, 0xffff0000, v29
	v_pk_fma_f32 v[30:31], v[146:147], v[18:19], v[158:159]
	v_pk_fma_f32 v[32:33], v[148:149], v[20:21], v[160:161]
	v_pk_fma_f32 v[34:35], v[134:135], v[6:7], v[154:155]
	v_pk_fma_f32 v[36:37], v[136:137], v[8:9], v[156:157]
	v_pk_fma_f32 v[30:31], v[142:143], v[14:15], v[30:31]
	v_pk_fma_f32 v[32:33], v[144:145], v[16:17], v[32:33]
	v_pk_fma_f32 v[34:35], v[130:131], v[2:3], v[34:35]
	v_pk_fma_f32 v[36:37], v[132:133], v[4:5], v[36:37]
	v_pk_fma_f32 v[30:31], v[150:151], v[22:23], v[30:31]
	v_pk_fma_f32 v[32:33], v[152:153], v[24:25], v[32:33]
	v_pk_fma_f32 v[34:35], v[138:139], v[10:11], v[34:35]
	v_pk_fma_f32 v[36:37], v[140:141], v[12:13], v[36:37]
	v_pk_mul_f32 v[42:43], v[30:31], s[6:7] op_sel_hi:[1,0]
	v_pk_mul_f32 v[44:45], v[32:33], s[6:7] op_sel_hi:[1,0]
	v_exp_f32_e32 v42, v42
	v_exp_f32_e32 v43, v43
	v_exp_f32_e32 v44, v44
	v_exp_f32_e32 v45, v45
	v_pk_add_f32 v[42:43], v[42:43], 1.0 op_sel_hi:[1,0]
	v_pk_add_f32 v[44:45], v[44:45], 1.0 op_sel_hi:[1,0]
	v_rcp_f32_e32 v46, v42
	v_rcp_f32_e32 v47, v43
	v_rcp_f32_e32 v48, v44
	v_rcp_f32_e32 v49, v45
	v_pk_mul_f32 v[46:47], v[30:31], v[46:47]
	v_pk_mul_f32 v[48:49], v[32:33], v[48:49]
	v_pk_mul_f32 v[34:35], v[34:35], v[46:47]
	v_pk_mul_f32 v[36:37], v[36:37], v[48:49]
	v_cvt_pk_bf16_f32 v66, v34, v35
	v_cvt_pk_bf16_f32 v67, v36, v37
	s_and_saveexec_b64 s[4:5], vcc
	global_store_dwordx2 v[58:59], v[66:67], off
	s_or_b64 exec, exec, s[4:5]
	v_lshl_add_u64 v[58:59], v[58:59], 0, v[56:57]
	s_branch .Lconv_done
